# cross attention chunk passes as two 4-iteration loops (code 3776 -> 1737 lines; running offsets and buffer toggles instead of unrolled immediates)
# speedup vs baseline: 1.0005x; 1.0005x over previous
; #define LAS __attribute__((address_space(3)))
; __device__ __forceinline__ int opaque_tid() { int t = (int)threadIdx.x; asm volatile("" : "+v"(t)); return t; }
; #define XLOAD(kvbase, c8) do { const bf16_t* _src = (kvbase) + (((c8) >= 4) ? 2048 : 0) + ((c8) & 3) * 128 + piece * 8; \
;         _Pragma("unroll") for (int _it = 0; _it < 8; ++_it) pre[_it] = *(const u32x4*)(_src + (size_t)(srow + 32 * _it) * 4096); } while (0)
; #define XSTORE(buf) do { _Pragma("unroll") for (int _it = 0; _it < 8; ++_it) *(LAS u32x4*)((buf) + (srow + 32 * _it) * KV_STRIDE + piece * 16) = pre[_it]; } while (0)
; __device__ void cross_items(const Params& p, LAS unsigned char* lds) {
;     const int tid = opaque_tid(), lane = tid & 63, w = __builtin_amdgcn_readfirstlane(tid >> 6), idx = lane & 15, g = lane >> 4;
;     unsigned char* ws = p.ws;
;     bf16_t* oc = (bf16_t*)(ws + OFF_OC);
;     const unsigned lbase = (unsigned)(size_t)lds;
;     const int piece = tid & 15, srow = tid >> 4;
;     const int G = (int)gridDim.x;
;     u32x4 pre[8];
;     ...
;     const int pmx = 8 * ((int)blockIdx.x & 7) + ((int)blockIdx.x >> 5), hdx = ((int)blockIdx.x >> 3) & 3;
;     const int item0 = (pmx >> 4) * 128 + hdx * 32 + 2 * (pmx & 15);
;     { const bf16_t* kvb0 = (const bf16_t*)(ws + OFF_MKV) + (size_t)((item0 >> 7) * 256) * 4096 + ((item0 >> 5) & 3) * 512; XLOAD(kvb0, 0); }
;     for (int item = item0; item < item0 + 2; ++item) {
;         const int b = item >> 7, head = (item >> 5) & 3, qb = item & 31;
;         const size_t tok = (size_t)(b * SEQ + qb * 128 + 16 * w + idx);
;         const bf16_t* qrow = (const bf16_t*)(ws + OFF_B1) + tok * DM + head * 512 + 8 * g;
;         const bf16_t* kvb = (const bf16_t*)(ws + OFF_MKV) + (size_t)(b * 256) * 4096 + head * 512;
;         f32x4 sc[16];
; #pragma unroll
;         for (int kt = 0; kt < 16; ++kt) sc[kt] = (f32x4){0.f, 0.f, 0.f, 0.f};
;         for (int c = 0; c < 4; ++c) {
;             LAS unsigned char* buf = lds + (c & 1) * KV_BUF;
;             XSTORE(buf);
;             bf16x8 qf[4];
; #pragma unroll
;             for (int ks = 0; ks < 4; ++ks) qf[ks] = *(const bf16x8*)(qrow + c * 128 + 32 * ks);
;             XLOAD(kvb, c + 1);
.LBB0_391:
	s_or_b64 exec, exec, s[0:1]
	v_mov_b32_e32 v40, v212
	s_waitcnt vmcnt(0) lgkmcnt(0)
	s_barrier
	v_readlane_b32 s0, v254, 29
	v_and_b32_e32 v243, 63, v212
	v_lshrrev_b32_e32 v242, 6, v212
	s_nop 1
	v_readfirstlane_b32 s4, v242
	s_lshr_b32 s0, s0, 9
	s_and_b32 s1, s0, 7
	s_lshl_b32 s1, s1, 3
	s_lshr_b32 s2, s0, 5
	s_add_i32 s1, s1, s2
	s_lshr_b32 s2, s0, 3
	s_and_b32 s2, s2, 3
	s_lshr_b32 s3, s1, 4
	s_add_u32 s6, s92, 0x1000
	s_addc_u32 s7, s93, 0
	v_and_b32_e32 v4, 15, v243
	v_lshrrev_b32_e32 v5, 4, v243
	v_and_b32_e32 v6, 15, v212
	v_lshrrev_b32_e32 v7, 4, v212
	v_and_b32_e32 v8, 7, v7
	v_lshl_add_u32 v8, v8, 1, v6
	v_and_b32_e32 v8, 15, v8
	v_lshlrev_b32_e32 v8, 4, v8
	v_lshl_add_u32 v0, v7, 8, v8
	v_add_u32_e32 v1, 0x10000, v0
	v_and_b32_e32 v9, 7, v4
	v_lshlrev_b32_e32 v9, 1, v9
	v_add_u32_e32 v9, v9, v5
	v_add_u32_e32 v10, 0, v9
	v_and_b32_e32 v10, 15, v10
	v_lshlrev_b32_e32 v10, 4, v10
	v_lshl_add_u32 v2, v4, 8, v10
	v_add_u32_e32 v10, 4, v9
	v_and_b32_e32 v10, 15, v10
	v_lshlrev_b32_e32 v10, 4, v10
	v_lshl_add_u32 v208, v4, 8, v10
	v_add_u32_e32 v10, 8, v9
	v_and_b32_e32 v10, 15, v10
	v_lshlrev_b32_e32 v10, 4, v10
	v_lshl_add_u32 v209, v4, 8, v10
	v_add_u32_e32 v10, 12, v9
	v_and_b32_e32 v10, 15, v10
	v_lshlrev_b32_e32 v10, 4, v10
	v_lshl_add_u32 v210, v4, 8, v10
	s_lshl_b32 s5, s1, 20
	s_lshl_b32 s8, s4, 16
	s_add_i32 s5, s5, s8
	s_lshl_b32 s8, s2, 10
	s_add_i32 s5, s5, s8
	v_lshlrev_b32_e32 v246, 12, v4
	v_add_u32_e32 v246, s5, v246
	v_lshl_add_u32 v248, v5, 3, v246
	v_add_u32_e32 v248, 0xd100000, v248
	v_add_u32_e32 v249, 0x80000, v248
	v_lshl_add_u32 v246, v5, 4, v246
	v_add_u32_e32 v247, 0x80000, v246
	s_lshl_b32 s5, s3, 21
	s_add_i32 s5, s5, s8
	s_add_i32 s5, s5, 0xc400000
	v_lshlrev_b32_e32 v242, 13, v7
	v_lshl_add_u32 v242, v6, 4, v242
	v_add_u32_e32 v242, s5, v242
	s_mov_b32 s9, 0
	s_and_b32 s2, s9, 3
	s_lshl_b32 s2, s2, 8
	s_lshr_b32 s3, s9, 2
	s_lshl_b32 s3, s3, 12
	s_add_i32 s2, s2, s3
	s_add_u32 s0, s92, s2
	s_addc_u32 s1, s93, 0
	s_add_i32 s9, s9, 1
	global_load_dwordx4 v[164:167], v242, s[0:1]
	v_add_u32_e32 v243, 0x40000, v242
	global_load_dwordx4 v[168:171], v243, s[0:1]
	v_add_u32_e32 v243, 0x80000, v242
	global_load_dwordx4 v[172:175], v243, s[0:1]
	v_add_u32_e32 v243, 0xc0000, v242
	global_load_dwordx4 v[176:179], v243, s[0:1]
	v_add_u32_e32 v243, 0x100000, v242
	global_load_dwordx4 v[180:183], v243, s[0:1]
	v_add_u32_e32 v243, 0x140000, v242
	global_load_dwordx4 v[184:187], v243, s[0:1]
	v_add_u32_e32 v243, 0x180000, v242
	global_load_dwordx4 v[188:191], v243, s[0:1]
	v_add_u32_e32 v243, 0x1c0000, v242
	global_load_dwordx4 v[192:195], v243, s[0:1]
	global_load_dwordx4 v[132:135], v246, s[92:93] offset:0
	global_load_dwordx4 v[136:139], v246, s[92:93] offset:64
	global_load_dwordx4 v[148:151], v247, s[92:93] offset:0
	global_load_dwordx4 v[152:155], v247, s[92:93] offset:64
	global_load_dwordx4 v[140:143], v246, s[92:93] offset:128
	global_load_dwordx4 v[144:147], v246, s[92:93] offset:192
	global_load_dwordx4 v[156:159], v247, s[92:93] offset:128
	global_load_dwordx4 v[160:163], v247, s[92:93] offset:192
	v_mov_b32_e32 v4, 0
	v_mov_b32_e32 v5, 0
	v_mov_b32_e32 v6, 0
	v_mov_b32_e32 v7, 0
	v_mov_b32_e32 v8, 0
	v_mov_b32_e32 v9, 0
	v_mov_b32_e32 v10, 0
	v_mov_b32_e32 v11, 0
	v_mov_b32_e32 v12, 0
	v_mov_b32_e32 v13, 0
	v_mov_b32_e32 v14, 0
	v_mov_b32_e32 v15, 0
	v_mov_b32_e32 v16, 0
	v_mov_b32_e32 v17, 0
	v_mov_b32_e32 v18, 0
	v_mov_b32_e32 v19, 0
	v_mov_b32_e32 v20, 0
	v_mov_b32_e32 v21, 0
	v_mov_b32_e32 v22, 0
	v_mov_b32_e32 v23, 0
	v_mov_b32_e32 v24, 0
	v_mov_b32_e32 v25, 0
	v_mov_b32_e32 v26, 0
	v_mov_b32_e32 v27, 0
	v_mov_b32_e32 v28, 0
	v_mov_b32_e32 v29, 0
	v_mov_b32_e32 v30, 0
	v_mov_b32_e32 v31, 0
	v_mov_b32_e32 v32, 0
	v_mov_b32_e32 v33, 0
	v_mov_b32_e32 v34, 0
	v_mov_b32_e32 v35, 0
	v_mov_b32_e32 v36, 0
	v_mov_b32_e32 v37, 0
	v_mov_b32_e32 v38, 0
	v_mov_b32_e32 v39, 0
	v_mov_b32_e32 v40, 0
	v_mov_b32_e32 v41, 0
	v_mov_b32_e32 v42, 0
	v_mov_b32_e32 v43, 0
	v_mov_b32_e32 v44, 0
	v_mov_b32_e32 v45, 0
	v_mov_b32_e32 v46, 0
	v_mov_b32_e32 v47, 0
	v_mov_b32_e32 v48, 0
	v_mov_b32_e32 v49, 0
	v_mov_b32_e32 v50, 0
	v_mov_b32_e32 v51, 0
	v_mov_b32_e32 v52, 0
	v_mov_b32_e32 v53, 0
	v_mov_b32_e32 v54, 0
	v_mov_b32_e32 v55, 0
	v_mov_b32_e32 v56, 0
	v_mov_b32_e32 v57, 0
	v_mov_b32_e32 v58, 0
	v_mov_b32_e32 v59, 0
	v_mov_b32_e32 v60, 0
	v_mov_b32_e32 v61, 0
	v_mov_b32_e32 v62, 0
	v_mov_b32_e32 v63, 0
	v_mov_b32_e32 v64, 0
	v_mov_b32_e32 v65, 0
	v_mov_b32_e32 v66, 0
	v_mov_b32_e32 v67, 0
	v_mov_b32_e32 v68, 0
	v_mov_b32_e32 v69, 0
	v_mov_b32_e32 v70, 0
	v_mov_b32_e32 v71, 0
	v_mov_b32_e32 v72, 0
	v_mov_b32_e32 v73, 0
	v_mov_b32_e32 v74, 0
	v_mov_b32_e32 v75, 0
	v_mov_b32_e32 v76, 0
	v_mov_b32_e32 v77, 0
	v_mov_b32_e32 v78, 0
	v_mov_b32_e32 v79, 0
	v_mov_b32_e32 v80, 0
	v_mov_b32_e32 v81, 0
	v_mov_b32_e32 v82, 0
	v_mov_b32_e32 v83, 0
	v_mov_b32_e32 v84, 0
	v_mov_b32_e32 v85, 0
	v_mov_b32_e32 v86, 0
	v_mov_b32_e32 v87, 0
	v_mov_b32_e32 v88, 0
	v_mov_b32_e32 v89, 0
	v_mov_b32_e32 v90, 0
	v_mov_b32_e32 v91, 0
	v_mov_b32_e32 v92, 0
	v_mov_b32_e32 v93, 0
	v_mov_b32_e32 v94, 0
	v_mov_b32_e32 v95, 0
	v_mov_b32_e32 v96, 0
	v_mov_b32_e32 v97, 0
	v_mov_b32_e32 v98, 0
	v_mov_b32_e32 v99, 0
	v_mov_b32_e32 v100, 0
	v_mov_b32_e32 v101, 0
	v_mov_b32_e32 v102, 0
	v_mov_b32_e32 v103, 0
	v_mov_b32_e32 v104, 0
	v_mov_b32_e32 v105, 0
	v_mov_b32_e32 v106, 0
	v_mov_b32_e32 v107, 0
	v_mov_b32_e32 v108, 0
	v_mov_b32_e32 v109, 0
	v_mov_b32_e32 v110, 0
	v_mov_b32_e32 v111, 0
	v_mov_b32_e32 v112, 0
	v_mov_b32_e32 v113, 0
	v_mov_b32_e32 v114, 0
	v_mov_b32_e32 v115, 0
	v_mov_b32_e32 v116, 0
	v_mov_b32_e32 v117, 0
	v_mov_b32_e32 v118, 0
	v_mov_b32_e32 v119, 0
	v_mov_b32_e32 v120, 0
	v_mov_b32_e32 v121, 0
	v_mov_b32_e32 v122, 0
	v_mov_b32_e32 v123, 0
	v_mov_b32_e32 v124, 0
	v_mov_b32_e32 v125, 0
	v_mov_b32_e32 v126, 0
	v_mov_b32_e32 v127, 0
	v_mov_b32_e32 v128, 0
	v_mov_b32_e32 v129, 0
	v_mov_b32_e32 v130, 0
	v_mov_b32_e32 v131, 0
	s_mov_b32 s4, 0
; #define LAS __attribute__((address_space(3)))
; __device__ __forceinline__ f32x4 mfma16(bf16x8 a, bf16x8 b, f32x4 c) { return __builtin_amdgcn_mfma_f32_16x16x32_bf16(a, b, c, 0, 0, 0); }
; #define LDS_BARRIER() do { asm volatile("s_waitcnt lgkmcnt(0)" ::: "memory"); __builtin_amdgcn_s_barrier(); asm volatile("" ::: "memory"); } while (0)
; #define XLOAD(kvbase, c8) do { const bf16_t* _src = (kvbase) + (((c8) >= 4) ? 2048 : 0) + ((c8) & 3) * 128 + piece * 8; \
;         _Pragma("unroll") for (int _it = 0; _it < 8; ++_it) pre[_it] = *(const u32x4*)(_src + (size_t)(srow + 32 * _it) * 4096); } while (0)
; #define XSTORE(buf) do { _Pragma("unroll") for (int _it = 0; _it < 8; ++_it) *(LAS u32x4*)((buf) + (srow + 32 * _it) * KV_STRIDE + piece * 16) = pre[_it]; } while (0)
; __device__ void cross_items(const Params& p, LAS unsigned char* lds) {
;     ...
;         for (int c = 0; c < 4; ++c) {
;             LAS unsigned char* buf = lds + (c & 1) * KV_BUF;
;             XSTORE(buf);
;             bf16x8 qf[4];
; #pragma unroll
;             for (int ks = 0; ks < 4; ++ks) qf[ks] = *(const bf16x8*)(qrow + c * 128 + 32 * ks);
;             XLOAD(kvb, c + 1);
;             LDS_BARRIER();
; #pragma unroll
;             for (int kt = 0; kt < 16; ++kt)
; #pragma unroll
;                 for (int ks = 0; ks < 4; ++ks) sc[kt] = mfma16(frag_row(buf, KV_STRIDE, 16 * kt, 32 * ks, idx, g), qf[ks], sc[kt]);
;         }
.Lxa_qk:
	s_waitcnt vmcnt(15)
	ds_write_b128 v0, v[164:167]
	s_waitcnt vmcnt(14)
	ds_write_b128 v0, v[168:171] offset:8192
	s_waitcnt vmcnt(13)
	ds_write_b128 v0, v[172:175] offset:16384
	s_waitcnt vmcnt(12)
	ds_write_b128 v0, v[176:179] offset:24576
	s_waitcnt vmcnt(11)
	ds_write_b128 v0, v[180:183] offset:32768
	s_waitcnt vmcnt(10)
	ds_write_b128 v0, v[184:187] offset:40960
	s_waitcnt vmcnt(9)
	ds_write_b128 v0, v[188:191] offset:49152
	s_waitcnt vmcnt(8)
	ds_write_b128 v0, v[192:195] offset:57344
	v_xor_b32_e32 v0, 0x10000, v0
	s_and_b32 s2, s9, 3
	s_lshl_b32 s2, s2, 8
	s_lshr_b32 s3, s9, 2
	s_lshl_b32 s3, s3, 12
	s_add_i32 s2, s2, s3
	s_add_u32 s0, s92, s2
	s_addc_u32 s1, s93, 0
	s_add_i32 s9, s9, 1
	global_load_dwordx4 v[164:167], v242, s[0:1]
	v_add_u32_e32 v243, 0x40000, v242
	global_load_dwordx4 v[168:171], v243, s[0:1]
	v_add_u32_e32 v243, 0x80000, v242
	global_load_dwordx4 v[172:175], v243, s[0:1]
	v_add_u32_e32 v243, 0xc0000, v242
	global_load_dwordx4 v[176:179], v243, s[0:1]
	v_add_u32_e32 v243, 0x100000, v242
	global_load_dwordx4 v[180:183], v243, s[0:1]
	v_add_u32_e32 v243, 0x140000, v242
	global_load_dwordx4 v[184:187], v243, s[0:1]
	v_add_u32_e32 v243, 0x180000, v242
	global_load_dwordx4 v[188:191], v243, s[0:1]
	v_add_u32_e32 v243, 0x1c0000, v242
	global_load_dwordx4 v[192:195], v243, s[0:1]
	s_waitcnt lgkmcnt(0)
	s_barrier
	ds_read_b128 v[196:199], v2
	ds_read_b128 v[200:203], v2 offset:4096
	ds_read_b128 v[204:207], v208
	ds_read_b128 v[220:223], v208 offset:4096
	ds_read_b128 v[230:233], v2 offset:8192
	ds_read_b128 v[234:237], v2 offset:12288
	ds_read_b128 v[238:241], v208 offset:8192
	s_waitcnt vmcnt(12) lgkmcnt(6)
	v_mfma_f32_16x16x32_bf16 v[4:7], v[196:199], v[132:135], v[4:7]
	v_mfma_f32_16x16x32_bf16 v[68:71], v[196:199], v[148:151], v[68:71]
	ds_read_b128 v[196:199], v208 offset:12288
	s_waitcnt lgkmcnt(6)
	v_mfma_f32_16x16x32_bf16 v[8:11], v[200:203], v[132:135], v[8:11]
	v_mfma_f32_16x16x32_bf16 v[72:75], v[200:203], v[148:151], v[72:75]
	ds_read_b128 v[200:203], v2 offset:16384
	s_waitcnt lgkmcnt(6)
	v_mfma_f32_16x16x32_bf16 v[4:7], v[204:207], v[136:139], v[4:7]
	v_mfma_f32_16x16x32_bf16 v[68:71], v[204:207], v[152:155], v[68:71]
	ds_read_b128 v[204:207], v2 offset:20480
	s_waitcnt lgkmcnt(6)
	v_mfma_f32_16x16x32_bf16 v[8:11], v[220:223], v[136:139], v[8:11]
	v_mfma_f32_16x16x32_bf16 v[72:75], v[220:223], v[152:155], v[72:75]
	ds_read_b128 v[220:223], v208 offset:16384
	s_waitcnt lgkmcnt(6)
	v_mfma_f32_16x16x32_bf16 v[12:15], v[230:233], v[132:135], v[12:15]
	v_mfma_f32_16x16x32_bf16 v[76:79], v[230:233], v[148:151], v[76:79]
	ds_read_b128 v[230:233], v208 offset:20480
	s_waitcnt lgkmcnt(6)
	v_mfma_f32_16x16x32_bf16 v[16:19], v[234:237], v[132:135], v[16:19]
	v_mfma_f32_16x16x32_bf16 v[80:83], v[234:237], v[148:151], v[80:83]
	ds_read_b128 v[234:237], v2 offset:24576
	s_waitcnt lgkmcnt(6)
	v_mfma_f32_16x16x32_bf16 v[12:15], v[238:241], v[136:139], v[12:15]
	v_mfma_f32_16x16x32_bf16 v[76:79], v[238:241], v[152:155], v[76:79]
	ds_read_b128 v[238:241], v2 offset:28672
	s_waitcnt lgkmcnt(6)
	v_mfma_f32_16x16x32_bf16 v[16:19], v[196:199], v[136:139], v[16:19]
	v_mfma_f32_16x16x32_bf16 v[80:83], v[196:199], v[152:155], v[80:83]
	ds_read_b128 v[196:199], v208 offset:24576
	s_waitcnt lgkmcnt(6)
	v_mfma_f32_16x16x32_bf16 v[20:23], v[200:203], v[132:135], v[20:23]
	v_mfma_f32_16x16x32_bf16 v[84:87], v[200:203], v[148:151], v[84:87]
	ds_read_b128 v[200:203], v208 offset:28672
	s_waitcnt lgkmcnt(6)
	v_mfma_f32_16x16x32_bf16 v[24:27], v[204:207], v[132:135], v[24:27]
	v_mfma_f32_16x16x32_bf16 v[88:91], v[204:207], v[148:151], v[88:91]
	ds_read_b128 v[204:207], v2 offset:32768
	s_waitcnt lgkmcnt(6)
	v_mfma_f32_16x16x32_bf16 v[20:23], v[220:223], v[136:139], v[20:23]
	v_mfma_f32_16x16x32_bf16 v[84:87], v[220:223], v[152:155], v[84:87]
	ds_read_b128 v[220:223], v2 offset:36864
	s_waitcnt lgkmcnt(6)
	v_mfma_f32_16x16x32_bf16 v[24:27], v[230:233], v[136:139], v[24:27]
	v_mfma_f32_16x16x32_bf16 v[88:91], v[230:233], v[152:155], v[88:91]
	ds_read_b128 v[230:233], v208 offset:32768
	s_waitcnt lgkmcnt(6)
	v_mfma_f32_16x16x32_bf16 v[28:31], v[234:237], v[132:135], v[28:31]
	v_mfma_f32_16x16x32_bf16 v[92:95], v[234:237], v[148:151], v[92:95]
	ds_read_b128 v[234:237], v208 offset:36864
	s_waitcnt lgkmcnt(6)
	v_mfma_f32_16x16x32_bf16 v[32:35], v[238:241], v[132:135], v[32:35]
	v_mfma_f32_16x16x32_bf16 v[96:99], v[238:241], v[148:151], v[96:99]
	ds_read_b128 v[238:241], v2 offset:40960
	s_waitcnt lgkmcnt(6)
	v_mfma_f32_16x16x32_bf16 v[28:31], v[196:199], v[136:139], v[28:31]
	v_mfma_f32_16x16x32_bf16 v[92:95], v[196:199], v[152:155], v[92:95]
	ds_read_b128 v[196:199], v2 offset:45056
	s_waitcnt lgkmcnt(6)
	v_mfma_f32_16x16x32_bf16 v[32:35], v[200:203], v[136:139], v[32:35]
	v_mfma_f32_16x16x32_bf16 v[96:99], v[200:203], v[152:155], v[96:99]
	ds_read_b128 v[200:203], v208 offset:40960
	s_waitcnt lgkmcnt(6)
	v_mfma_f32_16x16x32_bf16 v[36:39], v[204:207], v[132:135], v[36:39]
	v_mfma_f32_16x16x32_bf16 v[100:103], v[204:207], v[148:151], v[100:103]
	ds_read_b128 v[204:207], v208 offset:45056
	s_waitcnt lgkmcnt(6)
	v_mfma_f32_16x16x32_bf16 v[40:43], v[220:223], v[132:135], v[40:43]
	v_mfma_f32_16x16x32_bf16 v[104:107], v[220:223], v[148:151], v[104:107]
	ds_read_b128 v[220:223], v2 offset:49152
	s_waitcnt lgkmcnt(6)
	v_mfma_f32_16x16x32_bf16 v[36:39], v[230:233], v[136:139], v[36:39]
	v_mfma_f32_16x16x32_bf16 v[100:103], v[230:233], v[152:155], v[100:103]
	ds_read_b128 v[230:233], v2 offset:53248
	s_waitcnt lgkmcnt(6)
	v_mfma_f32_16x16x32_bf16 v[40:43], v[234:237], v[136:139], v[40:43]
	v_mfma_f32_16x16x32_bf16 v[104:107], v[234:237], v[152:155], v[104:107]
	ds_read_b128 v[234:237], v208 offset:49152
	s_waitcnt lgkmcnt(6)
; __device__ __forceinline__ f32x4 mfma16(bf16x8 a, bf16x8 b, f32x4 c) { return __builtin_amdgcn_mfma_f32_16x16x32_bf16(a, b, c, 0, 0, 0); }
; #define LDS_BARRIER() do { asm volatile("s_waitcnt lgkmcnt(0)" ::: "memory"); __builtin_amdgcn_s_barrier(); asm volatile("" ::: "memory"); } while (0)
; #define XLOAD(kvbase, c8) do { const bf16_t* _src = (kvbase) + (((c8) >= 4) ? 2048 : 0) + ((c8) & 3) * 128 + piece * 8; \
;         _Pragma("unroll") for (int _it = 0; _it < 8; ++_it) pre[_it] = *(const u32x4*)(_src + (size_t)(srow + 32 * _it) * 4096); } while (0)
; __device__ void cross_items(const Params& p, LAS unsigned char* lds) {
;     ...
;             for (int ks = 0; ks < 4; ++ks) qf[ks] = *(const bf16x8*)(qrow + c * 128 + 32 * ks);
;             XLOAD(kvb, c + 1);
;             LDS_BARRIER();
; #pragma unroll
;             for (int kt = 0; kt < 16; ++kt)
; #pragma unroll
;                 for (int ks = 0; ks < 4; ++ks) sc[kt] = mfma16(frag_row(buf, KV_STRIDE, 16 * kt, 32 * ks, idx, g), qf[ks], sc[kt]);
	v_mfma_f32_16x16x32_bf16 v[44:47], v[238:241], v[132:135], v[44:47]
	v_mfma_f32_16x16x32_bf16 v[108:111], v[238:241], v[148:151], v[108:111]
	ds_read_b128 v[238:241], v208 offset:53248
	s_waitcnt lgkmcnt(6)
	v_mfma_f32_16x16x32_bf16 v[48:51], v[196:199], v[132:135], v[48:51]
	v_mfma_f32_16x16x32_bf16 v[112:115], v[196:199], v[148:151], v[112:115]
	ds_read_b128 v[196:199], v2 offset:57344
	s_waitcnt lgkmcnt(6)
	v_mfma_f32_16x16x32_bf16 v[44:47], v[200:203], v[136:139], v[44:47]
	v_mfma_f32_16x16x32_bf16 v[108:111], v[200:203], v[152:155], v[108:111]
	ds_read_b128 v[200:203], v2 offset:61440
	s_waitcnt lgkmcnt(6)
	v_mfma_f32_16x16x32_bf16 v[48:51], v[204:207], v[136:139], v[48:51]
	v_mfma_f32_16x16x32_bf16 v[112:115], v[204:207], v[152:155], v[112:115]
	ds_read_b128 v[204:207], v208 offset:57344
	s_waitcnt lgkmcnt(6)
	v_mfma_f32_16x16x32_bf16 v[52:55], v[220:223], v[132:135], v[52:55]
	v_mfma_f32_16x16x32_bf16 v[116:119], v[220:223], v[148:151], v[116:119]
	ds_read_b128 v[220:223], v208 offset:61440
	s_waitcnt lgkmcnt(6)
	v_mfma_f32_16x16x32_bf16 v[56:59], v[230:233], v[132:135], v[56:59]
	v_mfma_f32_16x16x32_bf16 v[120:123], v[230:233], v[148:151], v[120:123]
	s_waitcnt lgkmcnt(5)
	v_mfma_f32_16x16x32_bf16 v[52:55], v[234:237], v[136:139], v[52:55]
	v_mfma_f32_16x16x32_bf16 v[116:119], v[234:237], v[152:155], v[116:119]
	s_waitcnt lgkmcnt(4)
	v_mfma_f32_16x16x32_bf16 v[56:59], v[238:241], v[136:139], v[56:59]
	v_mfma_f32_16x16x32_bf16 v[120:123], v[238:241], v[152:155], v[120:123]
	s_waitcnt lgkmcnt(3)
	v_mfma_f32_16x16x32_bf16 v[60:63], v[196:199], v[132:135], v[60:63]
	v_mfma_f32_16x16x32_bf16 v[124:127], v[196:199], v[148:151], v[124:127]
	s_waitcnt lgkmcnt(2)
	v_mfma_f32_16x16x32_bf16 v[64:67], v[200:203], v[132:135], v[64:67]
	v_mfma_f32_16x16x32_bf16 v[128:131], v[200:203], v[148:151], v[128:131]
	s_waitcnt lgkmcnt(1)
	v_mfma_f32_16x16x32_bf16 v[60:63], v[204:207], v[136:139], v[60:63]
	v_mfma_f32_16x16x32_bf16 v[124:127], v[204:207], v[152:155], v[124:127]
	s_waitcnt lgkmcnt(0)
	v_mfma_f32_16x16x32_bf16 v[64:67], v[220:223], v[136:139], v[64:67]
	v_mfma_f32_16x16x32_bf16 v[128:131], v[220:223], v[152:155], v[128:131]
	v_add_u32_e32 v246, 0x100, v246
	v_add_u32_e32 v247, 0x100, v247
	global_load_dwordx4 v[132:135], v246, s[92:93] offset:0
	global_load_dwordx4 v[136:139], v246, s[92:93] offset:64
	global_load_dwordx4 v[148:151], v247, s[92:93] offset:0
	global_load_dwordx4 v[152:155], v247, s[92:93] offset:64
	ds_read_b128 v[196:199], v209
	ds_read_b128 v[200:203], v209 offset:4096
	ds_read_b128 v[204:207], v210
	ds_read_b128 v[220:223], v210 offset:4096
	ds_read_b128 v[230:233], v209 offset:8192
	ds_read_b128 v[234:237], v209 offset:12288
	ds_read_b128 v[238:241], v210 offset:8192
	s_waitcnt vmcnt(12) lgkmcnt(6)
	v_mfma_f32_16x16x32_bf16 v[4:7], v[196:199], v[140:143], v[4:7]
	v_mfma_f32_16x16x32_bf16 v[68:71], v[196:199], v[156:159], v[68:71]
	ds_read_b128 v[196:199], v210 offset:12288
	s_waitcnt lgkmcnt(6)
	v_mfma_f32_16x16x32_bf16 v[8:11], v[200:203], v[140:143], v[8:11]
	v_mfma_f32_16x16x32_bf16 v[72:75], v[200:203], v[156:159], v[72:75]
	ds_read_b128 v[200:203], v209 offset:16384
	s_waitcnt lgkmcnt(6)
	v_mfma_f32_16x16x32_bf16 v[4:7], v[204:207], v[144:147], v[4:7]
	v_mfma_f32_16x16x32_bf16 v[68:71], v[204:207], v[160:163], v[68:71]
	ds_read_b128 v[204:207], v209 offset:20480
	s_waitcnt lgkmcnt(6)
	v_mfma_f32_16x16x32_bf16 v[8:11], v[220:223], v[144:147], v[8:11]
	v_mfma_f32_16x16x32_bf16 v[72:75], v[220:223], v[160:163], v[72:75]
	ds_read_b128 v[220:223], v210 offset:16384
	s_waitcnt lgkmcnt(6)
	v_mfma_f32_16x16x32_bf16 v[12:15], v[230:233], v[140:143], v[12:15]
	v_mfma_f32_16x16x32_bf16 v[76:79], v[230:233], v[156:159], v[76:79]
	ds_read_b128 v[230:233], v210 offset:20480
	s_waitcnt lgkmcnt(6)
	v_mfma_f32_16x16x32_bf16 v[16:19], v[234:237], v[140:143], v[16:19]
	v_mfma_f32_16x16x32_bf16 v[80:83], v[234:237], v[156:159], v[80:83]
	ds_read_b128 v[234:237], v209 offset:24576
	s_waitcnt lgkmcnt(6)
	v_mfma_f32_16x16x32_bf16 v[12:15], v[238:241], v[144:147], v[12:15]
	v_mfma_f32_16x16x32_bf16 v[76:79], v[238:241], v[160:163], v[76:79]
	ds_read_b128 v[238:241], v209 offset:28672
	s_waitcnt lgkmcnt(6)
	v_mfma_f32_16x16x32_bf16 v[16:19], v[196:199], v[144:147], v[16:19]
	v_mfma_f32_16x16x32_bf16 v[80:83], v[196:199], v[160:163], v[80:83]
	ds_read_b128 v[196:199], v210 offset:24576
	s_waitcnt lgkmcnt(6)
	v_mfma_f32_16x16x32_bf16 v[20:23], v[200:203], v[140:143], v[20:23]
	v_mfma_f32_16x16x32_bf16 v[84:87], v[200:203], v[156:159], v[84:87]
	ds_read_b128 v[200:203], v210 offset:28672
	s_waitcnt lgkmcnt(6)
	v_mfma_f32_16x16x32_bf16 v[24:27], v[204:207], v[140:143], v[24:27]
	v_mfma_f32_16x16x32_bf16 v[88:91], v[204:207], v[156:159], v[88:91]
	ds_read_b128 v[204:207], v209 offset:32768
	s_waitcnt lgkmcnt(6)
	v_mfma_f32_16x16x32_bf16 v[20:23], v[220:223], v[144:147], v[20:23]
	v_mfma_f32_16x16x32_bf16 v[84:87], v[220:223], v[160:163], v[84:87]
	ds_read_b128 v[220:223], v209 offset:36864
	s_waitcnt lgkmcnt(6)
	v_mfma_f32_16x16x32_bf16 v[24:27], v[230:233], v[144:147], v[24:27]
	v_mfma_f32_16x16x32_bf16 v[88:91], v[230:233], v[160:163], v[88:91]
	ds_read_b128 v[230:233], v210 offset:32768
	s_waitcnt lgkmcnt(6)
	v_mfma_f32_16x16x32_bf16 v[28:31], v[234:237], v[140:143], v[28:31]
	v_mfma_f32_16x16x32_bf16 v[92:95], v[234:237], v[156:159], v[92:95]
	ds_read_b128 v[234:237], v210 offset:36864
	s_waitcnt lgkmcnt(6)
	v_mfma_f32_16x16x32_bf16 v[32:35], v[238:241], v[140:143], v[32:35]
	v_mfma_f32_16x16x32_bf16 v[96:99], v[238:241], v[156:159], v[96:99]
	ds_read_b128 v[238:241], v209 offset:40960
	s_waitcnt lgkmcnt(6)
; __device__ __forceinline__ f32x4 mfma16(bf16x8 a, bf16x8 b, f32x4 c) { return __builtin_amdgcn_mfma_f32_16x16x32_bf16(a, b, c, 0, 0, 0); }
; __device__ void cross_items(const Params& p, LAS unsigned char* lds) {
;     ...
;             for (int kt = 0; kt < 16; ++kt)
; #pragma unroll
;                 for (int ks = 0; ks < 4; ++ks) sc[kt] = mfma16(frag_row(buf, KV_STRIDE, 16 * kt, 32 * ks, idx, g), qf[ks], sc[kt]);
;         }
;         const float scl = 0.04419417382415922f * LOG2E;
;         float mx = -1e30f;
; #pragma unroll
;         for (int kt = 0; kt < 16; ++kt)
; #pragma unroll
;             for (int rr = 0; rr < 4; ++rr) { const float sv = sc[kt][rr] * scl; sc[kt][rr] = sv; mx = fmaxf(mx, sv); }
;         mx = fmaxf(mx, __shfl_xor(mx, 16)); mx = fmaxf(mx, __shfl_xor(mx, 32));
	v_mfma_f32_16x16x32_bf16 v[28:31], v[196:199], v[144:147], v[28:31]
	v_mfma_f32_16x16x32_bf16 v[92:95], v[196:199], v[160:163], v[92:95]
	ds_read_b128 v[196:199], v209 offset:45056
	s_waitcnt lgkmcnt(6)
	v_mfma_f32_16x16x32_bf16 v[32:35], v[200:203], v[144:147], v[32:35]
	v_mfma_f32_16x16x32_bf16 v[96:99], v[200:203], v[160:163], v[96:99]
	ds_read_b128 v[200:203], v210 offset:40960
	s_waitcnt lgkmcnt(6)
	v_mfma_f32_16x16x32_bf16 v[36:39], v[204:207], v[140:143], v[36:39]
	v_mfma_f32_16x16x32_bf16 v[100:103], v[204:207], v[156:159], v[100:103]
	ds_read_b128 v[204:207], v210 offset:45056
	s_waitcnt lgkmcnt(6)
	v_mfma_f32_16x16x32_bf16 v[40:43], v[220:223], v[140:143], v[40:43]
	v_mfma_f32_16x16x32_bf16 v[104:107], v[220:223], v[156:159], v[104:107]
	ds_read_b128 v[220:223], v209 offset:49152
	s_waitcnt lgkmcnt(6)
	v_mfma_f32_16x16x32_bf16 v[36:39], v[230:233], v[144:147], v[36:39]
	v_mfma_f32_16x16x32_bf16 v[100:103], v[230:233], v[160:163], v[100:103]
	ds_read_b128 v[230:233], v209 offset:53248
	s_waitcnt lgkmcnt(6)
	v_mfma_f32_16x16x32_bf16 v[40:43], v[234:237], v[144:147], v[40:43]
	v_mfma_f32_16x16x32_bf16 v[104:107], v[234:237], v[160:163], v[104:107]
	ds_read_b128 v[234:237], v210 offset:49152
	s_waitcnt lgkmcnt(6)
	v_mfma_f32_16x16x32_bf16 v[44:47], v[238:241], v[140:143], v[44:47]
	v_mfma_f32_16x16x32_bf16 v[108:111], v[238:241], v[156:159], v[108:111]
	ds_read_b128 v[238:241], v210 offset:53248
	s_waitcnt lgkmcnt(6)
	v_mfma_f32_16x16x32_bf16 v[48:51], v[196:199], v[140:143], v[48:51]
	v_mfma_f32_16x16x32_bf16 v[112:115], v[196:199], v[156:159], v[112:115]
	ds_read_b128 v[196:199], v209 offset:57344
	s_waitcnt lgkmcnt(6)
	v_mfma_f32_16x16x32_bf16 v[44:47], v[200:203], v[144:147], v[44:47]
	v_mfma_f32_16x16x32_bf16 v[108:111], v[200:203], v[160:163], v[108:111]
	ds_read_b128 v[200:203], v209 offset:61440
	s_waitcnt lgkmcnt(6)
	v_mfma_f32_16x16x32_bf16 v[48:51], v[204:207], v[144:147], v[48:51]
	v_mfma_f32_16x16x32_bf16 v[112:115], v[204:207], v[160:163], v[112:115]
	ds_read_b128 v[204:207], v210 offset:57344
	s_waitcnt lgkmcnt(6)
	v_mfma_f32_16x16x32_bf16 v[52:55], v[220:223], v[140:143], v[52:55]
	v_mfma_f32_16x16x32_bf16 v[116:119], v[220:223], v[156:159], v[116:119]
	ds_read_b128 v[220:223], v210 offset:61440
	s_waitcnt lgkmcnt(6)
	v_mfma_f32_16x16x32_bf16 v[56:59], v[230:233], v[140:143], v[56:59]
	v_mfma_f32_16x16x32_bf16 v[120:123], v[230:233], v[156:159], v[120:123]
	s_waitcnt lgkmcnt(5)
	v_mfma_f32_16x16x32_bf16 v[52:55], v[234:237], v[144:147], v[52:55]
	v_mfma_f32_16x16x32_bf16 v[116:119], v[234:237], v[160:163], v[116:119]
	s_waitcnt lgkmcnt(4)
	v_mfma_f32_16x16x32_bf16 v[56:59], v[238:241], v[144:147], v[56:59]
	v_mfma_f32_16x16x32_bf16 v[120:123], v[238:241], v[160:163], v[120:123]
	s_waitcnt lgkmcnt(3)
	v_mfma_f32_16x16x32_bf16 v[60:63], v[196:199], v[140:143], v[60:63]
	v_mfma_f32_16x16x32_bf16 v[124:127], v[196:199], v[156:159], v[124:127]
	s_waitcnt lgkmcnt(2)
	v_mfma_f32_16x16x32_bf16 v[64:67], v[200:203], v[140:143], v[64:67]
	v_mfma_f32_16x16x32_bf16 v[128:131], v[200:203], v[156:159], v[128:131]
	s_waitcnt lgkmcnt(1)
	v_mfma_f32_16x16x32_bf16 v[60:63], v[204:207], v[144:147], v[60:63]
	v_mfma_f32_16x16x32_bf16 v[124:127], v[204:207], v[160:163], v[124:127]
	s_waitcnt lgkmcnt(0)
	v_mfma_f32_16x16x32_bf16 v[64:67], v[220:223], v[144:147], v[64:67]
	v_mfma_f32_16x16x32_bf16 v[128:131], v[220:223], v[160:163], v[128:131]
	global_load_dwordx4 v[140:143], v246, s[92:93] offset:128
	global_load_dwordx4 v[144:147], v246, s[92:93] offset:192
	global_load_dwordx4 v[156:159], v247, s[92:93] offset:128
	global_load_dwordx4 v[160:163], v247, s[92:93] offset:192
	v_xor_b32_e32 v2, 0x10000, v2
	v_xor_b32_e32 v208, 0x10000, v208
	v_xor_b32_e32 v209, 0x10000, v209
	v_xor_b32_e32 v210, 0x10000, v210
	s_add_i32 s4, s4, 1
	s_cmp_lt_u32 s4, 4
	s_cbranch_scc1 .Lxa_qk
	s_nop 7
	s_nop 7
	v_and_b32_e32 v199, 63, v212
	v_xor_b32_e32 v196, 16, v199
	v_lshlrev_b32_e32 v196, 2, v196
	v_xor_b32_e32 v197, 32, v199
	v_lshlrev_b32_e32 v197, 2, v197
	s_mov_b32 s5, 0x3d8293ee
	v_mov_b32_e32 v198, 0xf149f2ca
	v_mul_f32_e32 v199, 0x3d8293ee, v4
	v_mul_f32_e32 v200, 0x3d8293ee, v5
	v_max3_f32 v198, v198, v199, v200
	v_mul_f32_e32 v199, 0x3d8293ee, v6
	v_mul_f32_e32 v200, 0x3d8293ee, v7
	v_max3_f32 v198, v198, v199, v200
	v_mul_f32_e32 v199, 0x3d8293ee, v8
	v_mul_f32_e32 v200, 0x3d8293ee, v9
	v_max3_f32 v198, v198, v199, v200
	v_mul_f32_e32 v199, 0x3d8293ee, v10
	v_mul_f32_e32 v200, 0x3d8293ee, v11
	v_max3_f32 v198, v198, v199, v200
	v_mul_f32_e32 v199, 0x3d8293ee, v12
	v_mul_f32_e32 v200, 0x3d8293ee, v13
	v_max3_f32 v198, v198, v199, v200
	v_mul_f32_e32 v199, 0x3d8293ee, v14
	v_mul_f32_e32 v200, 0x3d8293ee, v15
	v_max3_f32 v198, v198, v199, v200
	v_mul_f32_e32 v199, 0x3d8293ee, v16
	v_mul_f32_e32 v200, 0x3d8293ee, v17
	v_max3_f32 v198, v198, v199, v200
	v_mul_f32_e32 v199, 0x3d8293ee, v18
	v_mul_f32_e32 v200, 0x3d8293ee, v19
	v_max3_f32 v198, v198, v199, v200
	v_mul_f32_e32 v199, 0x3d8293ee, v20
	v_mul_f32_e32 v200, 0x3d8293ee, v21
	v_max3_f32 v198, v198, v199, v200
	v_mul_f32_e32 v199, 0x3d8293ee, v22
	v_mul_f32_e32 v200, 0x3d8293ee, v23
	v_max3_f32 v198, v198, v199, v200
	v_mul_f32_e32 v199, 0x3d8293ee, v24
	v_mul_f32_e32 v200, 0x3d8293ee, v25
	v_max3_f32 v198, v198, v199, v200
	v_mul_f32_e32 v199, 0x3d8293ee, v26
	v_mul_f32_e32 v200, 0x3d8293ee, v27
	v_max3_f32 v198, v198, v199, v200
	v_mul_f32_e32 v199, 0x3d8293ee, v28
	v_mul_f32_e32 v200, 0x3d8293ee, v29
	v_max3_f32 v198, v198, v199, v200
	v_mul_f32_e32 v199, 0x3d8293ee, v30
	v_mul_f32_e32 v200, 0x3d8293ee, v31
	v_max3_f32 v198, v198, v199, v200
	v_mul_f32_e32 v199, 0x3d8293ee, v32
; __device__ __forceinline__ float fexp2(float x) { return __builtin_amdgcn_exp2f(x); }
; __device__ void cross_items(const Params& p, LAS unsigned char* lds) {
;     ...
;         float mx = -1e30f;
; #pragma unroll
;         for (int kt = 0; kt < 16; ++kt)
; #pragma unroll
;             for (int rr = 0; rr < 4; ++rr) { const float sv = sc[kt][rr] * scl; sc[kt][rr] = sv; mx = fmaxf(mx, sv); }
;         mx = fmaxf(mx, __shfl_xor(mx, 16)); mx = fmaxf(mx, __shfl_xor(mx, 32));
;         float sum = 0.f;
; #pragma unroll
;         for (int kt = 0; kt < 16; ++kt)
; #pragma unroll
;             for (int rr = 0; rr < 4; ++rr) { const float e = fexp2(sc[kt][rr] - mx); sc[kt][rr] = e; sum += e; }
	v_mul_f32_e32 v200, 0x3d8293ee, v33
	v_max3_f32 v198, v198, v199, v200
	v_mul_f32_e32 v199, 0x3d8293ee, v34
	v_mul_f32_e32 v200, 0x3d8293ee, v35
	v_max3_f32 v198, v198, v199, v200
	v_mul_f32_e32 v199, 0x3d8293ee, v36
	v_mul_f32_e32 v200, 0x3d8293ee, v37
	v_max3_f32 v198, v198, v199, v200
	v_mul_f32_e32 v199, 0x3d8293ee, v38
	v_mul_f32_e32 v200, 0x3d8293ee, v39
	v_max3_f32 v198, v198, v199, v200
	v_mul_f32_e32 v199, 0x3d8293ee, v40
	v_mul_f32_e32 v200, 0x3d8293ee, v41
	v_max3_f32 v198, v198, v199, v200
	v_mul_f32_e32 v199, 0x3d8293ee, v42
	v_mul_f32_e32 v200, 0x3d8293ee, v43
	v_max3_f32 v198, v198, v199, v200
	v_mul_f32_e32 v199, 0x3d8293ee, v44
	v_mul_f32_e32 v200, 0x3d8293ee, v45
	v_max3_f32 v198, v198, v199, v200
	v_mul_f32_e32 v199, 0x3d8293ee, v46
	v_mul_f32_e32 v200, 0x3d8293ee, v47
	v_max3_f32 v198, v198, v199, v200
	v_mul_f32_e32 v199, 0x3d8293ee, v48
	v_mul_f32_e32 v200, 0x3d8293ee, v49
	v_max3_f32 v198, v198, v199, v200
	v_mul_f32_e32 v199, 0x3d8293ee, v50
	v_mul_f32_e32 v200, 0x3d8293ee, v51
	v_max3_f32 v198, v198, v199, v200
	v_mul_f32_e32 v199, 0x3d8293ee, v52
	v_mul_f32_e32 v200, 0x3d8293ee, v53
	v_max3_f32 v198, v198, v199, v200
	v_mul_f32_e32 v199, 0x3d8293ee, v54
	v_mul_f32_e32 v200, 0x3d8293ee, v55
	v_max3_f32 v198, v198, v199, v200
	v_mul_f32_e32 v199, 0x3d8293ee, v56
	v_mul_f32_e32 v200, 0x3d8293ee, v57
	v_max3_f32 v198, v198, v199, v200
	v_mul_f32_e32 v199, 0x3d8293ee, v58
	v_mul_f32_e32 v200, 0x3d8293ee, v59
	v_max3_f32 v198, v198, v199, v200
	v_mul_f32_e32 v199, 0x3d8293ee, v60
	v_mul_f32_e32 v200, 0x3d8293ee, v61
	v_max3_f32 v198, v198, v199, v200
	v_mul_f32_e32 v199, 0x3d8293ee, v62
	v_mul_f32_e32 v200, 0x3d8293ee, v63
	v_max3_f32 v198, v198, v199, v200
	v_mul_f32_e32 v199, 0x3d8293ee, v64
	v_mul_f32_e32 v200, 0x3d8293ee, v65
	v_max3_f32 v198, v198, v199, v200
	v_mul_f32_e32 v199, 0x3d8293ee, v66
	v_mul_f32_e32 v200, 0x3d8293ee, v67
	v_max3_f32 v198, v198, v199, v200
	ds_bpermute_b32 v199, v196, v198
	s_waitcnt lgkmcnt(0)
	v_max_f32_e32 v198, v198, v199
	ds_bpermute_b32 v199, v197, v198
	s_waitcnt lgkmcnt(0)
	v_max_f32_e32 v198, v198, v199
	v_fma_f32 v4, v4, s5, -v198
	v_fma_f32 v5, v5, s5, -v198
	v_fma_f32 v6, v6, s5, -v198
	v_fma_f32 v7, v7, s5, -v198
	v_fma_f32 v8, v8, s5, -v198
	v_fma_f32 v9, v9, s5, -v198
	v_fma_f32 v10, v10, s5, -v198
	v_fma_f32 v11, v11, s5, -v198
	v_fma_f32 v12, v12, s5, -v198
	v_fma_f32 v13, v13, s5, -v198
	v_fma_f32 v14, v14, s5, -v198
	v_fma_f32 v15, v15, s5, -v198
	v_fma_f32 v16, v16, s5, -v198
	v_fma_f32 v17, v17, s5, -v198
	v_fma_f32 v18, v18, s5, -v198
	v_fma_f32 v19, v19, s5, -v198
	v_fma_f32 v20, v20, s5, -v198
	v_fma_f32 v21, v21, s5, -v198
	v_fma_f32 v22, v22, s5, -v198
	v_fma_f32 v23, v23, s5, -v198
	v_fma_f32 v24, v24, s5, -v198
	v_fma_f32 v25, v25, s5, -v198
	v_fma_f32 v26, v26, s5, -v198
	v_fma_f32 v27, v27, s5, -v198
	v_fma_f32 v28, v28, s5, -v198
	v_fma_f32 v29, v29, s5, -v198
	v_fma_f32 v30, v30, s5, -v198
	v_fma_f32 v31, v31, s5, -v198
	v_fma_f32 v32, v32, s5, -v198
	v_fma_f32 v33, v33, s5, -v198
	v_fma_f32 v34, v34, s5, -v198
	v_fma_f32 v35, v35, s5, -v198
	v_fma_f32 v36, v36, s5, -v198
	v_fma_f32 v37, v37, s5, -v198
	v_fma_f32 v38, v38, s5, -v198
	v_fma_f32 v39, v39, s5, -v198
	v_fma_f32 v40, v40, s5, -v198
	v_fma_f32 v41, v41, s5, -v198
	v_fma_f32 v42, v42, s5, -v198
	v_fma_f32 v43, v43, s5, -v198
	v_fma_f32 v44, v44, s5, -v198
	v_fma_f32 v45, v45, s5, -v198
	v_fma_f32 v46, v46, s5, -v198
	v_fma_f32 v47, v47, s5, -v198
	v_fma_f32 v48, v48, s5, -v198
	v_fma_f32 v49, v49, s5, -v198
	v_fma_f32 v50, v50, s5, -v198
	v_fma_f32 v51, v51, s5, -v198
	v_fma_f32 v52, v52, s5, -v198
	v_fma_f32 v53, v53, s5, -v198
	v_fma_f32 v54, v54, s5, -v198
	v_fma_f32 v55, v55, s5, -v198
	v_fma_f32 v56, v56, s5, -v198
	v_fma_f32 v57, v57, s5, -v198
	v_fma_f32 v58, v58, s5, -v198
	v_fma_f32 v59, v59, s5, -v198
	v_fma_f32 v60, v60, s5, -v198
	v_fma_f32 v61, v61, s5, -v198
	v_fma_f32 v62, v62, s5, -v198
	v_fma_f32 v63, v63, s5, -v198
	v_fma_f32 v64, v64, s5, -v198
	v_fma_f32 v65, v65, s5, -v198
	v_fma_f32 v66, v66, s5, -v198
	v_fma_f32 v67, v67, s5, -v198
	v_exp_f32_e32 v4, v4
	v_exp_f32_e32 v5, v5
	v_exp_f32_e32 v6, v6
	v_exp_f32_e32 v7, v7
	v_exp_f32_e32 v8, v8
	v_exp_f32_e32 v9, v9
	v_exp_f32_e32 v10, v10
	v_exp_f32_e32 v11, v11
	v_exp_f32_e32 v12, v12
	v_exp_f32_e32 v13, v13
	v_exp_f32_e32 v14, v14
	v_exp_f32_e32 v15, v15
	v_exp_f32_e32 v16, v16
	v_exp_f32_e32 v17, v17
	v_exp_f32_e32 v18, v18
	v_exp_f32_e32 v19, v19
	v_exp_f32_e32 v20, v20
	v_exp_f32_e32 v21, v21
	v_exp_f32_e32 v22, v22
	v_exp_f32_e32 v23, v23
	v_exp_f32_e32 v24, v24
	v_exp_f32_e32 v25, v25
	v_exp_f32_e32 v26, v26
	v_exp_f32_e32 v27, v27
	v_exp_f32_e32 v28, v28
	v_exp_f32_e32 v29, v29
	v_exp_f32_e32 v30, v30
	v_exp_f32_e32 v31, v31
	v_exp_f32_e32 v32, v32
	v_exp_f32_e32 v33, v33
	v_exp_f32_e32 v34, v34
	v_exp_f32_e32 v35, v35
	v_exp_f32_e32 v36, v36
	v_exp_f32_e32 v37, v37
	v_exp_f32_e32 v38, v38
	v_exp_f32_e32 v39, v39
	v_exp_f32_e32 v40, v40
	v_exp_f32_e32 v41, v41
	v_exp_f32_e32 v42, v42
	v_exp_f32_e32 v43, v43
	v_exp_f32_e32 v44, v44
	v_exp_f32_e32 v45, v45
	v_exp_f32_e32 v46, v46
	v_exp_f32_e32 v47, v47
	v_exp_f32_e32 v48, v48
	v_exp_f32_e32 v49, v49
	v_exp_f32_e32 v50, v50
	v_exp_f32_e32 v51, v51
	v_exp_f32_e32 v52, v52
	v_exp_f32_e32 v53, v53
	v_exp_f32_e32 v54, v54
	v_exp_f32_e32 v55, v55
	v_exp_f32_e32 v56, v56
	v_exp_f32_e32 v57, v57
	v_exp_f32_e32 v58, v58
	v_exp_f32_e32 v59, v59
	v_exp_f32_e32 v60, v60
	v_exp_f32_e32 v61, v61
	v_exp_f32_e32 v62, v62
	v_exp_f32_e32 v63, v63
	v_exp_f32_e32 v64, v64
	v_exp_f32_e32 v65, v65
	v_exp_f32_e32 v66, v66
	v_exp_f32_e32 v67, v67
	s_nop 0
	v_add_f32_e32 v201, 0, v4
; __device__ __forceinline__ unsigned cvt_pk_bf16(float lo, float hi) { const f32x2v v = {lo, hi}; const b16x2v r = __builtin_convertvector(v, b16x2v); return __builtin_bit_cast(unsigned, r); }
; __device__ __forceinline__ float fexp2(float x) { return __builtin_amdgcn_exp2f(x); }
; __device__ void cross_items(const Params& p, LAS unsigned char* lds) {
;     ...
; #pragma unroll
;         for (int kt = 0; kt < 16; ++kt)
; #pragma unroll
;             for (int rr = 0; rr < 4; ++rr) { const float e = fexp2(sc[kt][rr] - mx); sc[kt][rr] = e; sum += e; }
;         sum += __shfl_xor(sum, 16); sum += __shfl_xor(sum, 32);
;         const float inv = 1.0f / sum;
;         bf16x8 pf[8];
; #pragma unroll
;         for (int sx = 0; sx < 8; ++sx) { u32x4 pw; pw.x = cvt_pk_bf16(sc[2 * sx][0], sc[2 * sx][1]); pw.y = cvt_pk_bf16(sc[2 * sx][2], sc[2 * sx][3]); pw.z = cvt_pk_bf16(sc[2 * sx + 1][0], sc[2 * sx + 1][1]); pw.w = cvt_pk_bf16(sc[2 * sx + 1][2], sc[2 * sx + 1][3]);
;             pf[sx] = __builtin_bit_cast(bf16x8, pw); }
	v_add_f32_e32 v201, v5, v201
	v_add_f32_e32 v201, v6, v201
	v_add_f32_e32 v201, v7, v201
	v_add_f32_e32 v201, v8, v201
	v_add_f32_e32 v201, v9, v201
	v_add_f32_e32 v201, v10, v201
	v_add_f32_e32 v201, v11, v201
	v_add_f32_e32 v201, v12, v201
	v_add_f32_e32 v201, v13, v201
	v_add_f32_e32 v201, v14, v201
	v_add_f32_e32 v201, v15, v201
	v_add_f32_e32 v201, v16, v201
	v_add_f32_e32 v201, v17, v201
	v_add_f32_e32 v201, v18, v201
	v_add_f32_e32 v201, v19, v201
	v_add_f32_e32 v201, v20, v201
	v_add_f32_e32 v201, v21, v201
	v_add_f32_e32 v201, v22, v201
	v_add_f32_e32 v201, v23, v201
	v_add_f32_e32 v201, v24, v201
	v_add_f32_e32 v201, v25, v201
	v_add_f32_e32 v201, v26, v201
	v_add_f32_e32 v201, v27, v201
	v_add_f32_e32 v201, v28, v201
	v_add_f32_e32 v201, v29, v201
	v_add_f32_e32 v201, v30, v201
	v_add_f32_e32 v201, v31, v201
	v_add_f32_e32 v201, v32, v201
	v_add_f32_e32 v201, v33, v201
	v_add_f32_e32 v201, v34, v201
	v_add_f32_e32 v201, v35, v201
	v_add_f32_e32 v201, v36, v201
	v_add_f32_e32 v201, v37, v201
	v_add_f32_e32 v201, v38, v201
	v_add_f32_e32 v201, v39, v201
	v_add_f32_e32 v201, v40, v201
	v_add_f32_e32 v201, v41, v201
	v_add_f32_e32 v201, v42, v201
	v_add_f32_e32 v201, v43, v201
	v_add_f32_e32 v201, v44, v201
	v_add_f32_e32 v201, v45, v201
	v_add_f32_e32 v201, v46, v201
	v_add_f32_e32 v201, v47, v201
	v_add_f32_e32 v201, v48, v201
	v_add_f32_e32 v201, v49, v201
	v_add_f32_e32 v201, v50, v201
	v_add_f32_e32 v201, v51, v201
	v_add_f32_e32 v201, v52, v201
	v_add_f32_e32 v201, v53, v201
	v_add_f32_e32 v201, v54, v201
	v_add_f32_e32 v201, v55, v201
	v_add_f32_e32 v201, v56, v201
	v_add_f32_e32 v201, v57, v201
	v_add_f32_e32 v201, v58, v201
	v_add_f32_e32 v201, v59, v201
	v_add_f32_e32 v201, v60, v201
	v_add_f32_e32 v201, v61, v201
	v_add_f32_e32 v201, v62, v201
	v_add_f32_e32 v201, v63, v201
	v_add_f32_e32 v201, v64, v201
	v_add_f32_e32 v201, v65, v201
	v_add_f32_e32 v201, v66, v201
	v_add_f32_e32 v201, v67, v201
	ds_bpermute_b32 v199, v196, v201
	s_waitcnt lgkmcnt(0)
	v_add_f32_e32 v201, v201, v199
	ds_bpermute_b32 v199, v197, v201
	s_waitcnt lgkmcnt(0)
	v_add_f32_e32 v201, v201, v199
	v_div_scale_f32 v199, s[6:7], v201, v201, 1.0
	v_rcp_f32_e32 v200, v199
	s_nop 0
	v_fma_f32 v244, -v199, v200, 1.0
	v_fmac_f32_e32 v200, v244, v200
	v_div_scale_f32 v244, vcc, 1.0, v201, 1.0
	v_mul_f32_e32 v202, v244, v200
	v_fma_f32 v203, -v199, v202, v244
	v_fmac_f32_e32 v202, v203, v200
	v_fma_f32 v199, -v199, v202, v244
	s_nop 1
	v_div_fmas_f32 v199, v199, v200, v202
	v_div_fixup_f32 v244, v199, v201, 1.0
	v_cvt_pk_bf16_f32 v4, v4, v5
	v_cvt_pk_bf16_f32 v5, v6, v7
	v_cvt_pk_bf16_f32 v6, v8, v9
	v_cvt_pk_bf16_f32 v7, v10, v11
	v_cvt_pk_bf16_f32 v12, v12, v13
	v_cvt_pk_bf16_f32 v13, v14, v15
	v_cvt_pk_bf16_f32 v14, v16, v17
	v_cvt_pk_bf16_f32 v15, v18, v19
	v_cvt_pk_bf16_f32 v20, v20, v21
	v_cvt_pk_bf16_f32 v21, v22, v23
	v_cvt_pk_bf16_f32 v22, v24, v25
	v_cvt_pk_bf16_f32 v23, v26, v27
	v_cvt_pk_bf16_f32 v28, v28, v29
	v_cvt_pk_bf16_f32 v29, v30, v31
	v_cvt_pk_bf16_f32 v30, v32, v33
	v_cvt_pk_bf16_f32 v31, v34, v35
	v_cvt_pk_bf16_f32 v36, v36, v37
	v_cvt_pk_bf16_f32 v37, v38, v39
	v_cvt_pk_bf16_f32 v38, v40, v41
	v_cvt_pk_bf16_f32 v39, v42, v43
	v_cvt_pk_bf16_f32 v44, v44, v45
	v_cvt_pk_bf16_f32 v45, v46, v47
	v_cvt_pk_bf16_f32 v46, v48, v49
	v_cvt_pk_bf16_f32 v47, v50, v51
	v_cvt_pk_bf16_f32 v52, v52, v53
	v_cvt_pk_bf16_f32 v53, v54, v55
	v_cvt_pk_bf16_f32 v54, v56, v57
	v_cvt_pk_bf16_f32 v55, v58, v59
	v_cvt_pk_bf16_f32 v60, v60, v61
	v_cvt_pk_bf16_f32 v61, v62, v63
	v_cvt_pk_bf16_f32 v62, v64, v65
	v_cvt_pk_bf16_f32 v63, v66, v67
	v_mov_b32_e32 v198, 0xf149f2ca
	v_mul_f32_e32 v199, 0x3d8293ee, v68
	v_mul_f32_e32 v200, 0x3d8293ee, v69
	v_max3_f32 v198, v198, v199, v200
	v_mul_f32_e32 v199, 0x3d8293ee, v70
	v_mul_f32_e32 v200, 0x3d8293ee, v71
	v_max3_f32 v198, v198, v199, v200
	v_mul_f32_e32 v199, 0x3d8293ee, v72
	v_mul_f32_e32 v200, 0x3d8293ee, v73
	v_max3_f32 v198, v198, v199, v200
	v_mul_f32_e32 v199, 0x3d8293ee, v74
	v_mul_f32_e32 v200, 0x3d8293ee, v75
	v_max3_f32 v198, v198, v199, v200
	v_mul_f32_e32 v199, 0x3d8293ee, v76
	v_mul_f32_e32 v200, 0x3d8293ee, v77
	v_max3_f32 v198, v198, v199, v200
	v_mul_f32_e32 v199, 0x3d8293ee, v78
	v_mul_f32_e32 v200, 0x3d8293ee, v79
	v_max3_f32 v198, v198, v199, v200
	v_mul_f32_e32 v199, 0x3d8293ee, v80
	v_mul_f32_e32 v200, 0x3d8293ee, v81
	v_max3_f32 v198, v198, v199, v200
	v_mul_f32_e32 v199, 0x3d8293ee, v82
	v_mul_f32_e32 v200, 0x3d8293ee, v83
	v_max3_f32 v198, v198, v199, v200
	v_mul_f32_e32 v199, 0x3d8293ee, v84
	v_mul_f32_e32 v200, 0x3d8293ee, v85
	v_max3_f32 v198, v198, v199, v200
	v_mul_f32_e32 v199, 0x3d8293ee, v86
	v_mul_f32_e32 v200, 0x3d8293ee, v87
	v_max3_f32 v198, v198, v199, v200
	v_mul_f32_e32 v199, 0x3d8293ee, v88
	v_mul_f32_e32 v200, 0x3d8293ee, v89
	v_max3_f32 v198, v198, v199, v200
	v_mul_f32_e32 v199, 0x3d8293ee, v90
	v_mul_f32_e32 v200, 0x3d8293ee, v91
	v_max3_f32 v198, v198, v199, v200
	v_mul_f32_e32 v199, 0x3d8293ee, v92
	v_mul_f32_e32 v200, 0x3d8293ee, v93
	v_max3_f32 v198, v198, v199, v200
	v_mul_f32_e32 v199, 0x3d8293ee, v94
	v_mul_f32_e32 v200, 0x3d8293ee, v95
	v_max3_f32 v198, v198, v199, v200
	v_mul_f32_e32 v199, 0x3d8293ee, v96
	v_mul_f32_e32 v200, 0x3d8293ee, v97
	v_max3_f32 v198, v198, v199, v200
	v_mul_f32_e32 v199, 0x3d8293ee, v98
	v_mul_f32_e32 v200, 0x3d8293ee, v99
	v_max3_f32 v198, v198, v199, v200
	v_mul_f32_e32 v199, 0x3d8293ee, v100
	v_mul_f32_e32 v200, 0x3d8293ee, v101
	v_max3_f32 v198, v198, v199, v200
	v_mul_f32_e32 v199, 0x3d8293ee, v102
	v_mul_f32_e32 v200, 0x3d8293ee, v103
	v_max3_f32 v198, v198, v199, v200
	v_mul_f32_e32 v199, 0x3d8293ee, v104
	v_mul_f32_e32 v200, 0x3d8293ee, v105
; __device__ __forceinline__ float fexp2(float x) { return __builtin_amdgcn_exp2f(x); }
; __device__ void cross_items(const Params& p, LAS unsigned char* lds) {
;     ...
;         float mx = -1e30f;
; #pragma unroll
;         for (int kt = 0; kt < 16; ++kt)
; #pragma unroll
;             for (int rr = 0; rr < 4; ++rr) { const float sv = sc[kt][rr] * scl; sc[kt][rr] = sv; mx = fmaxf(mx, sv); }
;         mx = fmaxf(mx, __shfl_xor(mx, 16)); mx = fmaxf(mx, __shfl_xor(mx, 32));
;         float sum = 0.f;
; #pragma unroll
;         for (int kt = 0; kt < 16; ++kt)
; #pragma unroll
;             for (int rr = 0; rr < 4; ++rr) { const float e = fexp2(sc[kt][rr] - mx); sc[kt][rr] = e; sum += e; }
	v_max3_f32 v198, v198, v199, v200
	v_mul_f32_e32 v199, 0x3d8293ee, v106
	v_mul_f32_e32 v200, 0x3d8293ee, v107
	v_max3_f32 v198, v198, v199, v200
	v_mul_f32_e32 v199, 0x3d8293ee, v108
	v_mul_f32_e32 v200, 0x3d8293ee, v109
	v_max3_f32 v198, v198, v199, v200
	v_mul_f32_e32 v199, 0x3d8293ee, v110
	v_mul_f32_e32 v200, 0x3d8293ee, v111
	v_max3_f32 v198, v198, v199, v200
	v_mul_f32_e32 v199, 0x3d8293ee, v112
	v_mul_f32_e32 v200, 0x3d8293ee, v113
	v_max3_f32 v198, v198, v199, v200
	v_mul_f32_e32 v199, 0x3d8293ee, v114
	v_mul_f32_e32 v200, 0x3d8293ee, v115
	v_max3_f32 v198, v198, v199, v200
	v_mul_f32_e32 v199, 0x3d8293ee, v116
	v_mul_f32_e32 v200, 0x3d8293ee, v117
	v_max3_f32 v198, v198, v199, v200
	v_mul_f32_e32 v199, 0x3d8293ee, v118
	v_mul_f32_e32 v200, 0x3d8293ee, v119
	v_max3_f32 v198, v198, v199, v200
	v_mul_f32_e32 v199, 0x3d8293ee, v120
	v_mul_f32_e32 v200, 0x3d8293ee, v121
	v_max3_f32 v198, v198, v199, v200
	v_mul_f32_e32 v199, 0x3d8293ee, v122
	v_mul_f32_e32 v200, 0x3d8293ee, v123
	v_max3_f32 v198, v198, v199, v200
	v_mul_f32_e32 v199, 0x3d8293ee, v124
	v_mul_f32_e32 v200, 0x3d8293ee, v125
	v_max3_f32 v198, v198, v199, v200
	v_mul_f32_e32 v199, 0x3d8293ee, v126
	v_mul_f32_e32 v200, 0x3d8293ee, v127
	v_max3_f32 v198, v198, v199, v200
	v_mul_f32_e32 v199, 0x3d8293ee, v128
	v_mul_f32_e32 v200, 0x3d8293ee, v129
	v_max3_f32 v198, v198, v199, v200
	v_mul_f32_e32 v199, 0x3d8293ee, v130
	v_mul_f32_e32 v200, 0x3d8293ee, v131
	v_max3_f32 v198, v198, v199, v200
	ds_bpermute_b32 v199, v196, v198
	s_waitcnt lgkmcnt(0)
	v_max_f32_e32 v198, v198, v199
	ds_bpermute_b32 v199, v197, v198
	s_waitcnt lgkmcnt(0)
	v_max_f32_e32 v198, v198, v199
	v_fma_f32 v68, v68, s5, -v198
	v_fma_f32 v69, v69, s5, -v198
	v_fma_f32 v70, v70, s5, -v198
	v_fma_f32 v71, v71, s5, -v198
	v_fma_f32 v72, v72, s5, -v198
	v_fma_f32 v73, v73, s5, -v198
	v_fma_f32 v74, v74, s5, -v198
	v_fma_f32 v75, v75, s5, -v198
	v_fma_f32 v76, v76, s5, -v198
	v_fma_f32 v77, v77, s5, -v198
	v_fma_f32 v78, v78, s5, -v198
	v_fma_f32 v79, v79, s5, -v198
	v_fma_f32 v80, v80, s5, -v198
	v_fma_f32 v81, v81, s5, -v198
	v_fma_f32 v82, v82, s5, -v198
	v_fma_f32 v83, v83, s5, -v198
	v_fma_f32 v84, v84, s5, -v198
	v_fma_f32 v85, v85, s5, -v198
	v_fma_f32 v86, v86, s5, -v198
	v_fma_f32 v87, v87, s5, -v198
	v_fma_f32 v88, v88, s5, -v198
	v_fma_f32 v89, v89, s5, -v198
	v_fma_f32 v90, v90, s5, -v198
	v_fma_f32 v91, v91, s5, -v198
	v_fma_f32 v92, v92, s5, -v198
	v_fma_f32 v93, v93, s5, -v198
	v_fma_f32 v94, v94, s5, -v198
	v_fma_f32 v95, v95, s5, -v198
	v_fma_f32 v96, v96, s5, -v198
	v_fma_f32 v97, v97, s5, -v198
	v_fma_f32 v98, v98, s5, -v198
	v_fma_f32 v99, v99, s5, -v198
	v_fma_f32 v100, v100, s5, -v198
	v_fma_f32 v101, v101, s5, -v198
	v_fma_f32 v102, v102, s5, -v198
	v_fma_f32 v103, v103, s5, -v198
	v_fma_f32 v104, v104, s5, -v198
	v_fma_f32 v105, v105, s5, -v198
	v_fma_f32 v106, v106, s5, -v198
	v_fma_f32 v107, v107, s5, -v198
	v_fma_f32 v108, v108, s5, -v198
	v_fma_f32 v109, v109, s5, -v198
	v_fma_f32 v110, v110, s5, -v198
	v_fma_f32 v111, v111, s5, -v198
	v_fma_f32 v112, v112, s5, -v198
	v_fma_f32 v113, v113, s5, -v198
	v_fma_f32 v114, v114, s5, -v198
	v_fma_f32 v115, v115, s5, -v198
	v_fma_f32 v116, v116, s5, -v198
	v_fma_f32 v117, v117, s5, -v198
	v_fma_f32 v118, v118, s5, -v198
	v_fma_f32 v119, v119, s5, -v198
	v_fma_f32 v120, v120, s5, -v198
	v_fma_f32 v121, v121, s5, -v198
	v_fma_f32 v122, v122, s5, -v198
	v_fma_f32 v123, v123, s5, -v198
	v_fma_f32 v124, v124, s5, -v198
	v_fma_f32 v125, v125, s5, -v198
	v_fma_f32 v126, v126, s5, -v198
	v_fma_f32 v127, v127, s5, -v198
	v_fma_f32 v128, v128, s5, -v198
	v_fma_f32 v129, v129, s5, -v198
	v_fma_f32 v130, v130, s5, -v198
	v_fma_f32 v131, v131, s5, -v198
	v_exp_f32_e32 v68, v68
	v_exp_f32_e32 v69, v69
	v_exp_f32_e32 v70, v70
	v_exp_f32_e32 v71, v71
	v_exp_f32_e32 v72, v72
	v_exp_f32_e32 v73, v73
	v_exp_f32_e32 v74, v74
	v_exp_f32_e32 v75, v75
	v_exp_f32_e32 v76, v76
	v_exp_f32_e32 v77, v77
	v_exp_f32_e32 v78, v78
	v_exp_f32_e32 v79, v79
	v_exp_f32_e32 v80, v80
	v_exp_f32_e32 v81, v81
	v_exp_f32_e32 v82, v82
	v_exp_f32_e32 v83, v83
	v_exp_f32_e32 v84, v84
	v_exp_f32_e32 v85, v85
	v_exp_f32_e32 v86, v86
	v_exp_f32_e32 v87, v87
	v_exp_f32_e32 v88, v88
	v_exp_f32_e32 v89, v89
	v_exp_f32_e32 v90, v90
	v_exp_f32_e32 v91, v91
	v_exp_f32_e32 v92, v92
	v_exp_f32_e32 v93, v93
	v_exp_f32_e32 v94, v94
	v_exp_f32_e32 v95, v95
	v_exp_f32_e32 v96, v96
	v_exp_f32_e32 v97, v97
	v_exp_f32_e32 v98, v98
	v_exp_f32_e32 v99, v99
	v_exp_f32_e32 v100, v100
	v_exp_f32_e32 v101, v101
	v_exp_f32_e32 v102, v102
	v_exp_f32_e32 v103, v103
	v_exp_f32_e32 v104, v104
	v_exp_f32_e32 v105, v105
	v_exp_f32_e32 v106, v106
	v_exp_f32_e32 v107, v107
	v_exp_f32_e32 v108, v108
	v_exp_f32_e32 v109, v109
	v_exp_f32_e32 v110, v110
	v_exp_f32_e32 v111, v111
	v_exp_f32_e32 v112, v112
	v_exp_f32_e32 v113, v113
	v_exp_f32_e32 v114, v114
	v_exp_f32_e32 v115, v115
	v_exp_f32_e32 v116, v116
	v_exp_f32_e32 v117, v117
	v_exp_f32_e32 v118, v118
	v_exp_f32_e32 v119, v119
	v_exp_f32_e32 v120, v120
	v_exp_f32_e32 v121, v121
	v_exp_f32_e32 v122, v122
	v_exp_f32_e32 v123, v123
	v_exp_f32_e32 v124, v124
	v_exp_f32_e32 v125, v125
	v_exp_f32_e32 v126, v126
	v_exp_f32_e32 v127, v127
	v_exp_f32_e32 v128, v128
	v_exp_f32_e32 v129, v129
	v_exp_f32_e32 v130, v130
	v_exp_f32_e32 v131, v131
	s_nop 0
	v_add_f32_e32 v201, 0, v68
	v_add_f32_e32 v201, v69, v201
	v_add_f32_e32 v201, v70, v201
	v_add_f32_e32 v201, v71, v201
	v_add_f32_e32 v201, v72, v201
	v_add_f32_e32 v201, v73, v201
	v_add_f32_e32 v201, v74, v201
	v_add_f32_e32 v201, v75, v201
	v_add_f32_e32 v201, v76, v201
	v_add_f32_e32 v201, v77, v201
	v_add_f32_e32 v201, v78, v201
; #define LAS __attribute__((address_space(3)))
; __device__ __forceinline__ unsigned cvt_pk_bf16(float lo, float hi) { const f32x2v v = {lo, hi}; const b16x2v r = __builtin_convertvector(v, b16x2v); return __builtin_bit_cast(unsigned, r); }
; __device__ __forceinline__ float fexp2(float x) { return __builtin_amdgcn_exp2f(x); }
; #define LDS_BARRIER() do { asm volatile("s_waitcnt lgkmcnt(0)" ::: "memory"); __builtin_amdgcn_s_barrier(); asm volatile("" ::: "memory"); } while (0)
; #define XLOAD(kvbase, c8) do { const bf16_t* _src = (kvbase) + (((c8) >= 4) ? 2048 : 0) + ((c8) & 3) * 128 + piece * 8; \
;         _Pragma("unroll") for (int _it = 0; _it < 8; ++_it) pre[_it] = *(const u32x4*)(_src + (size_t)(srow + 32 * _it) * 4096); } while (0)
; __device__ void cross_items(const Params& p, LAS unsigned char* lds) {
;     ...
; #pragma unroll
;         for (int kt = 0; kt < 16; ++kt)
; #pragma unroll
;             for (int rr = 0; rr < 4; ++rr) { const float e = fexp2(sc[kt][rr] - mx); sc[kt][rr] = e; sum += e; }
;         sum += __shfl_xor(sum, 16); sum += __shfl_xor(sum, 32);
;         const float inv = 1.0f / sum;
;         bf16x8 pf[8];
; #pragma unroll
;         for (int sx = 0; sx < 8; ++sx) { u32x4 pw; pw.x = cvt_pk_bf16(sc[2 * sx][0], sc[2 * sx][1]); pw.y = cvt_pk_bf16(sc[2 * sx][2], sc[2 * sx][3]); pw.z = cvt_pk_bf16(sc[2 * sx + 1][0], sc[2 * sx + 1][1]); pw.w = cvt_pk_bf16(sc[2 * sx + 1][2], sc[2 * sx + 1][3]);
;             pf[sx] = __builtin_bit_cast(bf16x8, pw); }
;         const int nitem = (item + 1 < item0 + 2) ? item + 1 : 512;
;         const bf16_t* nkvb = (const bf16_t*)(ws + OFF_MKV) + (size_t)(((nitem < 512 ? nitem : item) >> 7) * 256) * 4096 + (((nitem < 512 ? nitem : item) >> 5) & 3) * 512;
;         for (int c = 0; c < 4; ++c) {
;             LAS unsigned char* buf = lds + (c & 1) * KV_BUF;
;             XSTORE(buf);
;             if (c < 3) XLOAD(kvb, 5 + c); else XLOAD(nkvb, 0);
;             LDS_BARRIER();
;             f32x4 ot[8];
; #pragma unroll
;             for (int c8 = 0; c8 < 8; ++c8) ot[c8] = (f32x4){0.f, 0.f, 0.f, 0.f};
;             const unsigned bb = lbase + (unsigned)((c & 1) * KV_BUF);
; #pragma unroll
;             for (int sx = 0; sx < 8; ++sx) {
;                 const unsigned aA = bb + (unsigned)((32 * sx + 4 * g + (idx >> 2)) * KV_STRIDE + 8 * (idx & 3));
;                 const unsigned aB = aA + 16u * KV_STRIDE;
	v_add_f32_e32 v201, v79, v201
	v_add_f32_e32 v201, v80, v201
	v_add_f32_e32 v201, v81, v201
	v_add_f32_e32 v201, v82, v201
	v_add_f32_e32 v201, v83, v201
	v_add_f32_e32 v201, v84, v201
	v_add_f32_e32 v201, v85, v201
	v_add_f32_e32 v201, v86, v201
	v_add_f32_e32 v201, v87, v201
	v_add_f32_e32 v201, v88, v201
	v_add_f32_e32 v201, v89, v201
	v_add_f32_e32 v201, v90, v201
	v_add_f32_e32 v201, v91, v201
	v_add_f32_e32 v201, v92, v201
	v_add_f32_e32 v201, v93, v201
	v_add_f32_e32 v201, v94, v201
	v_add_f32_e32 v201, v95, v201
	v_add_f32_e32 v201, v96, v201
	v_add_f32_e32 v201, v97, v201
	v_add_f32_e32 v201, v98, v201
	v_add_f32_e32 v201, v99, v201
	v_add_f32_e32 v201, v100, v201
	v_add_f32_e32 v201, v101, v201
	v_add_f32_e32 v201, v102, v201
	v_add_f32_e32 v201, v103, v201
	v_add_f32_e32 v201, v104, v201
	v_add_f32_e32 v201, v105, v201
	v_add_f32_e32 v201, v106, v201
	v_add_f32_e32 v201, v107, v201
	v_add_f32_e32 v201, v108, v201
	v_add_f32_e32 v201, v109, v201
	v_add_f32_e32 v201, v110, v201
	v_add_f32_e32 v201, v111, v201
	v_add_f32_e32 v201, v112, v201
	v_add_f32_e32 v201, v113, v201
	v_add_f32_e32 v201, v114, v201
	v_add_f32_e32 v201, v115, v201
	v_add_f32_e32 v201, v116, v201
	v_add_f32_e32 v201, v117, v201
	v_add_f32_e32 v201, v118, v201
	v_add_f32_e32 v201, v119, v201
	v_add_f32_e32 v201, v120, v201
	v_add_f32_e32 v201, v121, v201
	v_add_f32_e32 v201, v122, v201
	v_add_f32_e32 v201, v123, v201
	v_add_f32_e32 v201, v124, v201
	v_add_f32_e32 v201, v125, v201
	v_add_f32_e32 v201, v126, v201
	v_add_f32_e32 v201, v127, v201
	v_add_f32_e32 v201, v128, v201
	v_add_f32_e32 v201, v129, v201
	v_add_f32_e32 v201, v130, v201
	v_add_f32_e32 v201, v131, v201
	ds_bpermute_b32 v199, v196, v201
	s_waitcnt lgkmcnt(0)
	v_add_f32_e32 v201, v201, v199
	ds_bpermute_b32 v199, v197, v201
	s_waitcnt lgkmcnt(0)
	v_add_f32_e32 v201, v201, v199
	v_div_scale_f32 v199, s[6:7], v201, v201, 1.0
	v_rcp_f32_e32 v200, v199
	s_nop 0
	v_fma_f32 v245, -v199, v200, 1.0
	v_fmac_f32_e32 v200, v245, v200
	v_div_scale_f32 v245, vcc, 1.0, v201, 1.0
	v_mul_f32_e32 v202, v245, v200
	v_fma_f32 v203, -v199, v202, v245
	v_fmac_f32_e32 v202, v203, v200
	v_fma_f32 v199, -v199, v202, v245
	s_nop 1
	v_div_fmas_f32 v199, v199, v200, v202
	v_div_fixup_f32 v245, v199, v201, 1.0
	v_cvt_pk_bf16_f32 v68, v68, v69
	v_cvt_pk_bf16_f32 v69, v70, v71
	v_cvt_pk_bf16_f32 v70, v72, v73
	v_cvt_pk_bf16_f32 v71, v74, v75
	v_cvt_pk_bf16_f32 v76, v76, v77
	v_cvt_pk_bf16_f32 v77, v78, v79
	v_cvt_pk_bf16_f32 v78, v80, v81
	v_cvt_pk_bf16_f32 v79, v82, v83
	v_cvt_pk_bf16_f32 v84, v84, v85
	v_cvt_pk_bf16_f32 v85, v86, v87
	v_cvt_pk_bf16_f32 v86, v88, v89
	v_cvt_pk_bf16_f32 v87, v90, v91
	v_cvt_pk_bf16_f32 v92, v92, v93
	v_cvt_pk_bf16_f32 v93, v94, v95
	v_cvt_pk_bf16_f32 v94, v96, v97
	v_cvt_pk_bf16_f32 v95, v98, v99
	v_cvt_pk_bf16_f32 v100, v100, v101
	v_cvt_pk_bf16_f32 v101, v102, v103
	v_cvt_pk_bf16_f32 v102, v104, v105
	v_cvt_pk_bf16_f32 v103, v106, v107
	v_cvt_pk_bf16_f32 v108, v108, v109
	v_cvt_pk_bf16_f32 v109, v110, v111
	v_cvt_pk_bf16_f32 v110, v112, v113
	v_cvt_pk_bf16_f32 v111, v114, v115
	v_cvt_pk_bf16_f32 v116, v116, v117
	v_cvt_pk_bf16_f32 v117, v118, v119
	v_cvt_pk_bf16_f32 v118, v120, v121
	v_cvt_pk_bf16_f32 v119, v122, v123
	v_cvt_pk_bf16_f32 v124, v124, v125
	v_cvt_pk_bf16_f32 v125, v126, v127
	v_cvt_pk_bf16_f32 v126, v128, v129
	v_cvt_pk_bf16_f32 v127, v130, v131
	v_and_b32_e32 v204, 63, v212
	v_and_b32_e32 v205, 15, v204
	v_lshrrev_b32_e32 v204, 4, v204
	v_lshrrev_b32_e32 v206, 2, v205
	v_lshl_add_u32 v206, v204, 2, v206
	v_and_b32_e32 v207, 7, v206
	v_lshlrev_b32_e32 v207, 1, v207
	v_bfe_u32 v204, v205, 1, 1
	v_add_u32_e32 v207, v207, v204
	v_and_b32_e32 v204, 1, v205
	v_lshlrev_b32_e32 v204, 3, v204
	v_lshl_add_u32 v206, v206, 8, v204
	v_add_u32_e32 v204, 0, v207
	v_and_b32_e32 v204, 15, v204
	v_lshl_add_u32 v196, v204, 4, v206
	v_add_u32_e32 v204, 2, v207
	v_and_b32_e32 v204, 15, v204
	v_lshl_add_u32 v197, v204, 4, v206
	v_add_u32_e32 v204, 4, v207
	v_and_b32_e32 v204, 15, v204
	v_lshl_add_u32 v198, v204, 4, v206
	v_add_u32_e32 v204, 6, v207
	v_and_b32_e32 v204, 15, v204
	v_lshl_add_u32 v199, v204, 4, v206
	v_add_u32_e32 v204, 8, v207
	v_and_b32_e32 v204, 15, v204
	v_lshl_add_u32 v200, v204, 4, v206
	v_add_u32_e32 v204, 10, v207
	v_and_b32_e32 v204, 15, v204
	v_lshl_add_u32 v201, v204, 4, v206
	v_add_u32_e32 v204, 12, v207
	v_and_b32_e32 v204, 15, v204
	v_lshl_add_u32 v202, v204, 4, v206
	v_add_u32_e32 v204, 14, v207
	v_and_b32_e32 v204, 15, v204
	v_lshl_add_u32 v203, v204, 4, v206
	s_waitcnt vmcnt(0)
	s_mov_b32 s4, 0
; #define LAS __attribute__((address_space(3)))
; __device__ __forceinline__ f32x4 mfma16(bf16x8 a, bf16x8 b, f32x4 c) { return __builtin_amdgcn_mfma_f32_16x16x32_bf16(a, b, c, 0, 0, 0); }
; #define LDS_BARRIER() do { asm volatile("s_waitcnt lgkmcnt(0)" ::: "memory"); __builtin_amdgcn_s_barrier(); asm volatile("" ::: "memory"); } while (0)
; #define XLOAD(kvbase, c8) do { const bf16_t* _src = (kvbase) + (((c8) >= 4) ? 2048 : 0) + ((c8) & 3) * 128 + piece * 8; \
;         _Pragma("unroll") for (int _it = 0; _it < 8; ++_it) pre[_it] = *(const u32x4*)(_src + (size_t)(srow + 32 * _it) * 4096); } while (0)
; #define XSTORE(buf) do { _Pragma("unroll") for (int _it = 0; _it < 8; ++_it) *(LAS u32x4*)((buf) + (srow + 32 * _it) * KV_STRIDE + piece * 16) = pre[_it]; } while (0)
; __device__ void cross_items(const Params& p, LAS unsigned char* lds) {
;     ...
;         for (int c = 0; c < 4; ++c) {
;             LAS unsigned char* buf = lds + (c & 1) * KV_BUF;
;             XSTORE(buf);
;             if (c < 3) XLOAD(kvb, 5 + c); else XLOAD(nkvb, 0);
;             LDS_BARRIER();
;             f32x4 ot[8];
; #pragma unroll
;             for (int c8 = 0; c8 < 8; ++c8) ot[c8] = (f32x4){0.f, 0.f, 0.f, 0.f};
;             const unsigned bb = lbase + (unsigned)((c & 1) * KV_BUF);
; #pragma unroll
;             for (int sx = 0; sx < 8; ++sx) {
;                 const unsigned aA = bb + (unsigned)((32 * sx + 4 * g + (idx >> 2)) * KV_STRIDE + 8 * (idx & 3));
;                 const unsigned aB = aA + 16u * KV_STRIDE;
;                 bf16x8 vf[4];
;                 tr_frag4(aA, aB, vf);
; #pragma unroll
;                 for (int c8 = 0; c8 < 4; ++c8) ot[c8] = mfma16(vf[c8], pf[sx], ot[c8]);
;                 tr_frag4(aA + 128, aB + 128, vf);
; #pragma unroll
;                 for (int c8 = 0; c8 < 4; ++c8) ot[4 + c8] = mfma16(vf[c8], pf[sx], ot[4 + c8]);
;             }
.Lxa_pv:
	s_waitcnt vmcnt(23)
	ds_write_b128 v0, v[164:167]
	s_waitcnt vmcnt(22)
	ds_write_b128 v0, v[168:171] offset:8192
	s_waitcnt vmcnt(21)
	ds_write_b128 v0, v[172:175] offset:16384
	s_waitcnt vmcnt(20)
	ds_write_b128 v0, v[176:179] offset:24576
	s_waitcnt vmcnt(19)
	ds_write_b128 v0, v[180:183] offset:32768
	s_waitcnt vmcnt(18)
	ds_write_b128 v0, v[184:187] offset:40960
	s_waitcnt vmcnt(17)
	ds_write_b128 v0, v[188:191] offset:49152
	s_waitcnt vmcnt(16)
	ds_write_b128 v0, v[192:195] offset:57344
	v_xor_b32_e32 v0, 0x10000, v0
	s_and_b32 s2, s9, 3
	s_lshl_b32 s2, s2, 8
	s_lshr_b32 s3, s9, 2
	s_lshl_b32 s3, s3, 12
	s_add_i32 s2, s2, s3
	s_add_u32 s0, s92, s2
	s_addc_u32 s1, s93, 0
	s_add_i32 s9, s9, 1
	global_load_dwordx4 v[164:167], v242, s[0:1]
	v_add_u32_e32 v243, 0x40000, v242
	global_load_dwordx4 v[168:171], v243, s[0:1]
	v_add_u32_e32 v243, 0x80000, v242
	global_load_dwordx4 v[172:175], v243, s[0:1]
	v_add_u32_e32 v243, 0xc0000, v242
	global_load_dwordx4 v[176:179], v243, s[0:1]
	v_add_u32_e32 v243, 0x100000, v242
	global_load_dwordx4 v[180:183], v243, s[0:1]
	v_add_u32_e32 v243, 0x140000, v242
	global_load_dwordx4 v[184:187], v243, s[0:1]
	v_add_u32_e32 v243, 0x180000, v242
	global_load_dwordx4 v[188:191], v243, s[0:1]
	v_add_u32_e32 v243, 0x1c0000, v242
	global_load_dwordx4 v[192:195], v243, s[0:1]
	s_waitcnt lgkmcnt(0)
	s_barrier
	ds_read_b64_tr_b16 v[72:73], v196
	ds_read_b64_tr_b16 v[80:81], v197
	ds_read_b64_tr_b16 v[74:75], v196 offset:4096
	ds_read_b64_tr_b16 v[82:83], v197 offset:4096
	ds_read_b64_tr_b16 v[88:89], v198
	ds_read_b64_tr_b16 v[96:97], v199
	ds_read_b64_tr_b16 v[90:91], v198 offset:4096
	ds_read_b64_tr_b16 v[98:99], v199 offset:4096
	ds_read_b64_tr_b16 v[104:105], v200
	ds_read_b64_tr_b16 v[112:113], v201
	ds_read_b64_tr_b16 v[106:107], v200 offset:4096
	ds_read_b64_tr_b16 v[114:115], v201 offset:4096
	s_waitcnt lgkmcnt(8)
	ds_read_b64_tr_b16 v[120:121], v202
	ds_read_b64_tr_b16 v[128:129], v203
	ds_read_b64_tr_b16 v[122:123], v202 offset:4096
	ds_read_b64_tr_b16 v[130:131], v203 offset:4096
	v_mfma_f32_16x16x32_bf16 v[132:135], v[72:75], v[4:7], 0
	v_mfma_f32_16x16x32_bf16 v[8:11], v[72:75], v[68:71], 0
	v_mfma_f32_16x16x32_bf16 v[136:139], v[80:83], v[4:7], 0
	v_mfma_f32_16x16x32_bf16 v[16:19], v[80:83], v[68:71], 0
	s_waitcnt lgkmcnt(8)
	ds_read_b64_tr_b16 v[72:73], v196 offset:8192
	ds_read_b64_tr_b16 v[80:81], v197 offset:8192
	ds_read_b64_tr_b16 v[74:75], v196 offset:12288
	ds_read_b64_tr_b16 v[82:83], v197 offset:12288
	v_mfma_f32_16x16x32_bf16 v[140:143], v[88:91], v[4:7], 0
	v_mfma_f32_16x16x32_bf16 v[24:27], v[88:91], v[68:71], 0
	v_mfma_f32_16x16x32_bf16 v[144:147], v[96:99], v[4:7], 0
	v_mfma_f32_16x16x32_bf16 v[32:35], v[96:99], v[68:71], 0
	s_waitcnt lgkmcnt(8)
	ds_read_b64_tr_b16 v[88:89], v198 offset:8192
	ds_read_b64_tr_b16 v[96:97], v199 offset:8192
	ds_read_b64_tr_b16 v[90:91], v198 offset:12288
	ds_read_b64_tr_b16 v[98:99], v199 offset:12288
	v_mfma_f32_16x16x32_bf16 v[148:151], v[104:107], v[4:7], 0
	v_mfma_f32_16x16x32_bf16 v[40:43], v[104:107], v[68:71], 0
	v_mfma_f32_16x16x32_bf16 v[152:155], v[112:115], v[4:7], 0
	v_mfma_f32_16x16x32_bf16 v[48:51], v[112:115], v[68:71], 0
	s_waitcnt lgkmcnt(8)
	ds_read_b64_tr_b16 v[104:105], v200 offset:8192
	ds_read_b64_tr_b16 v[112:113], v201 offset:8192
	ds_read_b64_tr_b16 v[106:107], v200 offset:12288
	ds_read_b64_tr_b16 v[114:115], v201 offset:12288
	v_mfma_f32_16x16x32_bf16 v[156:159], v[120:123], v[4:7], 0
	v_mfma_f32_16x16x32_bf16 v[56:59], v[120:123], v[68:71], 0
	v_mfma_f32_16x16x32_bf16 v[160:163], v[128:131], v[4:7], 0
	v_mfma_f32_16x16x32_bf16 v[64:67], v[128:131], v[68:71], 0
	s_waitcnt lgkmcnt(8)
	ds_read_b64_tr_b16 v[120:121], v202 offset:8192
	ds_read_b64_tr_b16 v[128:129], v203 offset:8192
	ds_read_b64_tr_b16 v[122:123], v202 offset:12288
	ds_read_b64_tr_b16 v[130:131], v203 offset:12288
	v_mfma_f32_16x16x32_bf16 v[132:135], v[72:75], v[12:15], v[132:135]
	v_mfma_f32_16x16x32_bf16 v[8:11], v[72:75], v[76:79], v[8:11]
	v_mfma_f32_16x16x32_bf16 v[136:139], v[80:83], v[12:15], v[136:139]
	v_mfma_f32_16x16x32_bf16 v[16:19], v[80:83], v[76:79], v[16:19]
	s_waitcnt lgkmcnt(8)
	ds_read_b64_tr_b16 v[72:73], v196 offset:16384
	ds_read_b64_tr_b16 v[80:81], v197 offset:16384
	ds_read_b64_tr_b16 v[74:75], v196 offset:20480
	ds_read_b64_tr_b16 v[82:83], v197 offset:20480
	v_mfma_f32_16x16x32_bf16 v[140:143], v[88:91], v[12:15], v[140:143]
	v_mfma_f32_16x16x32_bf16 v[24:27], v[88:91], v[76:79], v[24:27]
	v_mfma_f32_16x16x32_bf16 v[144:147], v[96:99], v[12:15], v[144:147]
	v_mfma_f32_16x16x32_bf16 v[32:35], v[96:99], v[76:79], v[32:35]
	s_waitcnt lgkmcnt(8)
	ds_read_b64_tr_b16 v[88:89], v198 offset:16384
	ds_read_b64_tr_b16 v[96:97], v199 offset:16384
	ds_read_b64_tr_b16 v[90:91], v198 offset:20480
	ds_read_b64_tr_b16 v[98:99], v199 offset:20480
	v_mfma_f32_16x16x32_bf16 v[148:151], v[104:107], v[12:15], v[148:151]
	v_mfma_f32_16x16x32_bf16 v[40:43], v[104:107], v[76:79], v[40:43]
	v_mfma_f32_16x16x32_bf16 v[152:155], v[112:115], v[12:15], v[152:155]
	v_mfma_f32_16x16x32_bf16 v[48:51], v[112:115], v[76:79], v[48:51]
	s_waitcnt lgkmcnt(8)
	ds_read_b64_tr_b16 v[104:105], v200 offset:16384
	ds_read_b64_tr_b16 v[112:113], v201 offset:16384
	ds_read_b64_tr_b16 v[106:107], v200 offset:20480
	ds_read_b64_tr_b16 v[114:115], v201 offset:20480
	v_mfma_f32_16x16x32_bf16 v[156:159], v[120:123], v[12:15], v[156:159]
	v_mfma_f32_16x16x32_bf16 v[56:59], v[120:123], v[76:79], v[56:59]
	v_mfma_f32_16x16x32_bf16 v[160:163], v[128:131], v[12:15], v[160:163]
	v_mfma_f32_16x16x32_bf16 v[64:67], v[128:131], v[76:79], v[64:67]
	s_waitcnt lgkmcnt(8)
; __device__ __forceinline__ f32x4 mfma16(bf16x8 a, bf16x8 b, f32x4 c) { return __builtin_amdgcn_mfma_f32_16x16x32_bf16(a, b, c, 0, 0, 0); }
; __device__ void cross_items(const Params& p, LAS unsigned char* lds) {
;     ...
; #pragma unroll
;             for (int sx = 0; sx < 8; ++sx) {
;                 const unsigned aA = bb + (unsigned)((32 * sx + 4 * g + (idx >> 2)) * KV_STRIDE + 8 * (idx & 3));
;                 const unsigned aB = aA + 16u * KV_STRIDE;
;                 bf16x8 vf[4];
;                 tr_frag4(aA, aB, vf);
; #pragma unroll
;                 for (int c8 = 0; c8 < 4; ++c8) ot[c8] = mfma16(vf[c8], pf[sx], ot[c8]);
;                 tr_frag4(aA + 128, aB + 128, vf);
; #pragma unroll
;                 for (int c8 = 0; c8 < 4; ++c8) ot[4 + c8] = mfma16(vf[c8], pf[sx], ot[4 + c8]);
;             }
	ds_read_b64_tr_b16 v[120:121], v202 offset:16384
	ds_read_b64_tr_b16 v[128:129], v203 offset:16384
	ds_read_b64_tr_b16 v[122:123], v202 offset:20480
	ds_read_b64_tr_b16 v[130:131], v203 offset:20480
	v_mfma_f32_16x16x32_bf16 v[132:135], v[72:75], v[20:23], v[132:135]
	v_mfma_f32_16x16x32_bf16 v[8:11], v[72:75], v[84:87], v[8:11]
	v_mfma_f32_16x16x32_bf16 v[136:139], v[80:83], v[20:23], v[136:139]
	v_mfma_f32_16x16x32_bf16 v[16:19], v[80:83], v[84:87], v[16:19]
	s_waitcnt lgkmcnt(8)
	ds_read_b64_tr_b16 v[72:73], v196 offset:24576
	ds_read_b64_tr_b16 v[80:81], v197 offset:24576
	ds_read_b64_tr_b16 v[74:75], v196 offset:28672
	ds_read_b64_tr_b16 v[82:83], v197 offset:28672
	v_mfma_f32_16x16x32_bf16 v[140:143], v[88:91], v[20:23], v[140:143]
	v_mfma_f32_16x16x32_bf16 v[24:27], v[88:91], v[84:87], v[24:27]
	v_mfma_f32_16x16x32_bf16 v[144:147], v[96:99], v[20:23], v[144:147]
	v_mfma_f32_16x16x32_bf16 v[32:35], v[96:99], v[84:87], v[32:35]
	s_waitcnt lgkmcnt(8)
	ds_read_b64_tr_b16 v[88:89], v198 offset:24576
	ds_read_b64_tr_b16 v[96:97], v199 offset:24576
	ds_read_b64_tr_b16 v[90:91], v198 offset:28672
	ds_read_b64_tr_b16 v[98:99], v199 offset:28672
	v_mfma_f32_16x16x32_bf16 v[148:151], v[104:107], v[20:23], v[148:151]
	v_mfma_f32_16x16x32_bf16 v[40:43], v[104:107], v[84:87], v[40:43]
	v_mfma_f32_16x16x32_bf16 v[152:155], v[112:115], v[20:23], v[152:155]
	v_mfma_f32_16x16x32_bf16 v[48:51], v[112:115], v[84:87], v[48:51]
	s_waitcnt lgkmcnt(8)
	ds_read_b64_tr_b16 v[104:105], v200 offset:24576
	ds_read_b64_tr_b16 v[112:113], v201 offset:24576
	ds_read_b64_tr_b16 v[106:107], v200 offset:28672
	ds_read_b64_tr_b16 v[114:115], v201 offset:28672
	v_mfma_f32_16x16x32_bf16 v[156:159], v[120:123], v[20:23], v[156:159]
	v_mfma_f32_16x16x32_bf16 v[56:59], v[120:123], v[84:87], v[56:59]
	v_mfma_f32_16x16x32_bf16 v[160:163], v[128:131], v[20:23], v[160:163]
	v_mfma_f32_16x16x32_bf16 v[64:67], v[128:131], v[84:87], v[64:67]
	s_waitcnt lgkmcnt(8)
	ds_read_b64_tr_b16 v[120:121], v202 offset:24576
	ds_read_b64_tr_b16 v[128:129], v203 offset:24576
	ds_read_b64_tr_b16 v[122:123], v202 offset:28672
	ds_read_b64_tr_b16 v[130:131], v203 offset:28672
	v_mfma_f32_16x16x32_bf16 v[132:135], v[72:75], v[28:31], v[132:135]
	v_mfma_f32_16x16x32_bf16 v[8:11], v[72:75], v[92:95], v[8:11]
	v_mfma_f32_16x16x32_bf16 v[136:139], v[80:83], v[28:31], v[136:139]
	v_mfma_f32_16x16x32_bf16 v[16:19], v[80:83], v[92:95], v[16:19]
	s_waitcnt lgkmcnt(8)
	ds_read_b64_tr_b16 v[72:73], v196 offset:32768
	ds_read_b64_tr_b16 v[80:81], v197 offset:32768
	ds_read_b64_tr_b16 v[74:75], v196 offset:36864
	ds_read_b64_tr_b16 v[82:83], v197 offset:36864
	v_mfma_f32_16x16x32_bf16 v[140:143], v[88:91], v[28:31], v[140:143]
	v_mfma_f32_16x16x32_bf16 v[24:27], v[88:91], v[92:95], v[24:27]
	v_mfma_f32_16x16x32_bf16 v[144:147], v[96:99], v[28:31], v[144:147]
	v_mfma_f32_16x16x32_bf16 v[32:35], v[96:99], v[92:95], v[32:35]
	s_waitcnt lgkmcnt(8)
	ds_read_b64_tr_b16 v[88:89], v198 offset:32768
	ds_read_b64_tr_b16 v[96:97], v199 offset:32768
	ds_read_b64_tr_b16 v[90:91], v198 offset:36864
	ds_read_b64_tr_b16 v[98:99], v199 offset:36864
	v_mfma_f32_16x16x32_bf16 v[148:151], v[104:107], v[28:31], v[148:151]
	v_mfma_f32_16x16x32_bf16 v[40:43], v[104:107], v[92:95], v[40:43]
	v_mfma_f32_16x16x32_bf16 v[152:155], v[112:115], v[28:31], v[152:155]
	v_mfma_f32_16x16x32_bf16 v[48:51], v[112:115], v[92:95], v[48:51]
	s_waitcnt lgkmcnt(8)
	ds_read_b64_tr_b16 v[104:105], v200 offset:32768
	ds_read_b64_tr_b16 v[112:113], v201 offset:32768
	ds_read_b64_tr_b16 v[106:107], v200 offset:36864
	ds_read_b64_tr_b16 v[114:115], v201 offset:36864
	v_mfma_f32_16x16x32_bf16 v[156:159], v[120:123], v[28:31], v[156:159]
	v_mfma_f32_16x16x32_bf16 v[56:59], v[120:123], v[92:95], v[56:59]
	v_mfma_f32_16x16x32_bf16 v[160:163], v[128:131], v[28:31], v[160:163]
	v_mfma_f32_16x16x32_bf16 v[64:67], v[128:131], v[92:95], v[64:67]
	s_waitcnt lgkmcnt(8)
	ds_read_b64_tr_b16 v[120:121], v202 offset:32768
	ds_read_b64_tr_b16 v[128:129], v203 offset:32768
	ds_read_b64_tr_b16 v[122:123], v202 offset:36864
	ds_read_b64_tr_b16 v[130:131], v203 offset:36864
	v_mfma_f32_16x16x32_bf16 v[132:135], v[72:75], v[36:39], v[132:135]
	v_mfma_f32_16x16x32_bf16 v[8:11], v[72:75], v[100:103], v[8:11]
	v_mfma_f32_16x16x32_bf16 v[136:139], v[80:83], v[36:39], v[136:139]
	v_mfma_f32_16x16x32_bf16 v[16:19], v[80:83], v[100:103], v[16:19]
	s_waitcnt lgkmcnt(8)
	ds_read_b64_tr_b16 v[72:73], v196 offset:40960
	ds_read_b64_tr_b16 v[80:81], v197 offset:40960
	ds_read_b64_tr_b16 v[74:75], v196 offset:45056
	ds_read_b64_tr_b16 v[82:83], v197 offset:45056
	v_mfma_f32_16x16x32_bf16 v[140:143], v[88:91], v[36:39], v[140:143]
	v_mfma_f32_16x16x32_bf16 v[24:27], v[88:91], v[100:103], v[24:27]
	v_mfma_f32_16x16x32_bf16 v[144:147], v[96:99], v[36:39], v[144:147]
	v_mfma_f32_16x16x32_bf16 v[32:35], v[96:99], v[100:103], v[32:35]
	s_waitcnt lgkmcnt(8)
	ds_read_b64_tr_b16 v[88:89], v198 offset:40960
	ds_read_b64_tr_b16 v[96:97], v199 offset:40960
	ds_read_b64_tr_b16 v[90:91], v198 offset:45056
	ds_read_b64_tr_b16 v[98:99], v199 offset:45056
	v_mfma_f32_16x16x32_bf16 v[148:151], v[104:107], v[36:39], v[148:151]
	v_mfma_f32_16x16x32_bf16 v[40:43], v[104:107], v[100:103], v[40:43]
	v_mfma_f32_16x16x32_bf16 v[152:155], v[112:115], v[36:39], v[152:155]
	v_mfma_f32_16x16x32_bf16 v[48:51], v[112:115], v[100:103], v[48:51]
	s_waitcnt lgkmcnt(8)
	ds_read_b64_tr_b16 v[104:105], v200 offset:40960
	ds_read_b64_tr_b16 v[112:113], v201 offset:40960
	ds_read_b64_tr_b16 v[106:107], v200 offset:45056
	ds_read_b64_tr_b16 v[114:115], v201 offset:45056
	v_mfma_f32_16x16x32_bf16 v[156:159], v[120:123], v[36:39], v[156:159]
	v_mfma_f32_16x16x32_bf16 v[56:59], v[120:123], v[100:103], v[56:59]
	v_mfma_f32_16x16x32_bf16 v[160:163], v[128:131], v[36:39], v[160:163]
	v_mfma_f32_16x16x32_bf16 v[64:67], v[128:131], v[100:103], v[64:67]
	s_waitcnt lgkmcnt(8)
; __device__ __forceinline__ f32x4 mfma16(bf16x8 a, bf16x8 b, f32x4 c) { return __builtin_amdgcn_mfma_f32_16x16x32_bf16(a, b, c, 0, 0, 0); }
; __device__ void cross_items(const Params& p, LAS unsigned char* lds) {
;     ...
; #pragma unroll
;             for (int sx = 0; sx < 8; ++sx) {
;                 const unsigned aA = bb + (unsigned)((32 * sx + 4 * g + (idx >> 2)) * KV_STRIDE + 8 * (idx & 3));
;                 const unsigned aB = aA + 16u * KV_STRIDE;
;                 bf16x8 vf[4];
;                 tr_frag4(aA, aB, vf);
; #pragma unroll
;                 for (int c8 = 0; c8 < 4; ++c8) ot[c8] = mfma16(vf[c8], pf[sx], ot[c8]);
;                 tr_frag4(aA + 128, aB + 128, vf);
; #pragma unroll
;                 for (int c8 = 0; c8 < 4; ++c8) ot[4 + c8] = mfma16(vf[c8], pf[sx], ot[4 + c8]);
;             }
	ds_read_b64_tr_b16 v[120:121], v202 offset:40960
	ds_read_b64_tr_b16 v[128:129], v203 offset:40960
	ds_read_b64_tr_b16 v[122:123], v202 offset:45056
	ds_read_b64_tr_b16 v[130:131], v203 offset:45056
	v_mfma_f32_16x16x32_bf16 v[132:135], v[72:75], v[44:47], v[132:135]
	v_mfma_f32_16x16x32_bf16 v[8:11], v[72:75], v[108:111], v[8:11]
	v_mfma_f32_16x16x32_bf16 v[136:139], v[80:83], v[44:47], v[136:139]
	v_mfma_f32_16x16x32_bf16 v[16:19], v[80:83], v[108:111], v[16:19]
	s_waitcnt lgkmcnt(8)
	ds_read_b64_tr_b16 v[72:73], v196 offset:49152
	ds_read_b64_tr_b16 v[80:81], v197 offset:49152
	ds_read_b64_tr_b16 v[74:75], v196 offset:53248
	ds_read_b64_tr_b16 v[82:83], v197 offset:53248
	v_mfma_f32_16x16x32_bf16 v[140:143], v[88:91], v[44:47], v[140:143]
	v_mfma_f32_16x16x32_bf16 v[24:27], v[88:91], v[108:111], v[24:27]
	v_mfma_f32_16x16x32_bf16 v[144:147], v[96:99], v[44:47], v[144:147]
	v_mfma_f32_16x16x32_bf16 v[32:35], v[96:99], v[108:111], v[32:35]
	s_waitcnt lgkmcnt(8)
	ds_read_b64_tr_b16 v[88:89], v198 offset:49152
	ds_read_b64_tr_b16 v[96:97], v199 offset:49152
	ds_read_b64_tr_b16 v[90:91], v198 offset:53248
	ds_read_b64_tr_b16 v[98:99], v199 offset:53248
	v_mfma_f32_16x16x32_bf16 v[148:151], v[104:107], v[44:47], v[148:151]
	v_mfma_f32_16x16x32_bf16 v[40:43], v[104:107], v[108:111], v[40:43]
	v_mfma_f32_16x16x32_bf16 v[152:155], v[112:115], v[44:47], v[152:155]
	v_mfma_f32_16x16x32_bf16 v[48:51], v[112:115], v[108:111], v[48:51]
	s_waitcnt lgkmcnt(8)
	ds_read_b64_tr_b16 v[104:105], v200 offset:49152
	ds_read_b64_tr_b16 v[112:113], v201 offset:49152
	ds_read_b64_tr_b16 v[106:107], v200 offset:53248
	ds_read_b64_tr_b16 v[114:115], v201 offset:53248
	v_mfma_f32_16x16x32_bf16 v[156:159], v[120:123], v[44:47], v[156:159]
	v_mfma_f32_16x16x32_bf16 v[56:59], v[120:123], v[108:111], v[56:59]
	v_mfma_f32_16x16x32_bf16 v[160:163], v[128:131], v[44:47], v[160:163]
	v_mfma_f32_16x16x32_bf16 v[64:67], v[128:131], v[108:111], v[64:67]
	s_waitcnt lgkmcnt(8)
	ds_read_b64_tr_b16 v[120:121], v202 offset:49152
	ds_read_b64_tr_b16 v[128:129], v203 offset:49152
	ds_read_b64_tr_b16 v[122:123], v202 offset:53248
	ds_read_b64_tr_b16 v[130:131], v203 offset:53248
	v_mfma_f32_16x16x32_bf16 v[132:135], v[72:75], v[52:55], v[132:135]
	v_mfma_f32_16x16x32_bf16 v[8:11], v[72:75], v[116:119], v[8:11]
	v_mfma_f32_16x16x32_bf16 v[136:139], v[80:83], v[52:55], v[136:139]
	v_mfma_f32_16x16x32_bf16 v[16:19], v[80:83], v[116:119], v[16:19]
	s_waitcnt lgkmcnt(8)
	ds_read_b64_tr_b16 v[72:73], v196 offset:57344
	ds_read_b64_tr_b16 v[80:81], v197 offset:57344
	ds_read_b64_tr_b16 v[74:75], v196 offset:61440
	ds_read_b64_tr_b16 v[82:83], v197 offset:61440
	v_mfma_f32_16x16x32_bf16 v[140:143], v[88:91], v[52:55], v[140:143]
	v_mfma_f32_16x16x32_bf16 v[24:27], v[88:91], v[116:119], v[24:27]
	v_mfma_f32_16x16x32_bf16 v[144:147], v[96:99], v[52:55], v[144:147]
	v_mfma_f32_16x16x32_bf16 v[32:35], v[96:99], v[116:119], v[32:35]
	s_waitcnt lgkmcnt(8)
	ds_read_b64_tr_b16 v[88:89], v198 offset:57344
	ds_read_b64_tr_b16 v[96:97], v199 offset:57344
	ds_read_b64_tr_b16 v[90:91], v198 offset:61440
	ds_read_b64_tr_b16 v[98:99], v199 offset:61440
	v_mfma_f32_16x16x32_bf16 v[148:151], v[104:107], v[52:55], v[148:151]
	v_mfma_f32_16x16x32_bf16 v[40:43], v[104:107], v[116:119], v[40:43]
	v_mfma_f32_16x16x32_bf16 v[152:155], v[112:115], v[52:55], v[152:155]
	v_mfma_f32_16x16x32_bf16 v[48:51], v[112:115], v[116:119], v[48:51]
	s_waitcnt lgkmcnt(8)
	ds_read_b64_tr_b16 v[104:105], v200 offset:57344
	ds_read_b64_tr_b16 v[112:113], v201 offset:57344
	ds_read_b64_tr_b16 v[106:107], v200 offset:61440
	ds_read_b64_tr_b16 v[114:115], v201 offset:61440
	v_mfma_f32_16x16x32_bf16 v[156:159], v[120:123], v[52:55], v[156:159]
	v_mfma_f32_16x16x32_bf16 v[56:59], v[120:123], v[116:119], v[56:59]
	v_mfma_f32_16x16x32_bf16 v[160:163], v[128:131], v[52:55], v[160:163]
	v_mfma_f32_16x16x32_bf16 v[64:67], v[128:131], v[116:119], v[64:67]
	s_waitcnt lgkmcnt(8)
	ds_read_b64_tr_b16 v[120:121], v202 offset:57344
	ds_read_b64_tr_b16 v[128:129], v203 offset:57344
	ds_read_b64_tr_b16 v[122:123], v202 offset:61440
	ds_read_b64_tr_b16 v[130:131], v203 offset:61440
	v_mfma_f32_16x16x32_bf16 v[132:135], v[72:75], v[60:63], v[132:135]
	v_mfma_f32_16x16x32_bf16 v[8:11], v[72:75], v[124:127], v[8:11]
	v_mfma_f32_16x16x32_bf16 v[136:139], v[80:83], v[60:63], v[136:139]
	v_mfma_f32_16x16x32_bf16 v[16:19], v[80:83], v[124:127], v[16:19]
	s_waitcnt lgkmcnt(8)
	v_mfma_f32_16x16x32_bf16 v[140:143], v[88:91], v[60:63], v[140:143]
	v_mfma_f32_16x16x32_bf16 v[24:27], v[88:91], v[124:127], v[24:27]
	v_mfma_f32_16x16x32_bf16 v[144:147], v[96:99], v[60:63], v[144:147]
	v_mfma_f32_16x16x32_bf16 v[32:35], v[96:99], v[124:127], v[32:35]
	s_waitcnt lgkmcnt(4)
	v_mfma_f32_16x16x32_bf16 v[148:151], v[104:107], v[60:63], v[148:151]
	v_mfma_f32_16x16x32_bf16 v[40:43], v[104:107], v[124:127], v[40:43]
	v_mfma_f32_16x16x32_bf16 v[152:155], v[112:115], v[60:63], v[152:155]
	v_mfma_f32_16x16x32_bf16 v[48:51], v[112:115], v[124:127], v[48:51]
	s_waitcnt lgkmcnt(0)
; __device__ __forceinline__ unsigned cvt_pk_bf16(float lo, float hi) { const f32x2v v = {lo, hi}; const b16x2v r = __builtin_convertvector(v, b16x2v); return __builtin_bit_cast(unsigned, r); }
; __device__ void cross_items(const Params& p, LAS unsigned char* lds) {
;     ...
; #pragma unroll
;             for (int c8 = 0; c8 < 8; ++c8) { u32x2 wv; wv.x = cvt_pk_bf16(ot[c8][0] * inv, ot[c8][1] * inv); wv.y = cvt_pk_bf16(ot[c8][2] * inv, ot[c8][3] * inv);
;                 *(u32x2*)(oc + tok * DM + head * 512 + c * 128 + 16 * c8 + 4 * g) = wv; }
;         }
;     }
;     ...
;     asm volatile("s_waitcnt vmcnt(0)" ::: "memory");
;     __syncthreads();
	v_mfma_f32_16x16x32_bf16 v[156:159], v[120:123], v[60:63], v[156:159]
	v_mfma_f32_16x16x32_bf16 v[56:59], v[120:123], v[124:127], v[56:59]
	v_mfma_f32_16x16x32_bf16 v[160:163], v[128:131], v[60:63], v[160:163]
	v_mfma_f32_16x16x32_bf16 v[64:67], v[128:131], v[124:127], v[64:67]
	s_nop 7
	s_nop 7
	v_mul_f32_e32 v230, v244, v132
	v_mul_f32_e32 v231, v244, v133
	v_mul_f32_e32 v232, v244, v134
	v_mul_f32_e32 v233, v244, v135
	v_cvt_pk_bf16_f32 v230, v230, v231
	v_cvt_pk_bf16_f32 v231, v232, v233
	global_store_dwordx2 v248, v[230:231], s[92:93]
	v_mul_f32_e32 v234, v244, v136
	v_mul_f32_e32 v235, v244, v137
	v_mul_f32_e32 v236, v244, v138
	v_mul_f32_e32 v237, v244, v139
	v_cvt_pk_bf16_f32 v234, v234, v235
	v_cvt_pk_bf16_f32 v235, v236, v237
	global_store_dwordx2 v248, v[234:235], s[92:93] offset:32
	v_mul_f32_e32 v230, v244, v140
	v_mul_f32_e32 v231, v244, v141
	v_mul_f32_e32 v232, v244, v142
	v_mul_f32_e32 v233, v244, v143
	v_cvt_pk_bf16_f32 v230, v230, v231
	v_cvt_pk_bf16_f32 v231, v232, v233
	global_store_dwordx2 v248, v[230:231], s[92:93] offset:64
	v_mul_f32_e32 v234, v244, v144
	v_mul_f32_e32 v235, v244, v145
	v_mul_f32_e32 v236, v244, v146
	v_mul_f32_e32 v237, v244, v147
	v_cvt_pk_bf16_f32 v234, v234, v235
	v_cvt_pk_bf16_f32 v235, v236, v237
	global_store_dwordx2 v248, v[234:235], s[92:93] offset:96
	v_mul_f32_e32 v230, v244, v148
	v_mul_f32_e32 v231, v244, v149
	v_mul_f32_e32 v232, v244, v150
	v_mul_f32_e32 v233, v244, v151
	v_cvt_pk_bf16_f32 v230, v230, v231
	v_cvt_pk_bf16_f32 v231, v232, v233
	global_store_dwordx2 v248, v[230:231], s[92:93] offset:128
	v_mul_f32_e32 v234, v244, v152
	v_mul_f32_e32 v235, v244, v153
	v_mul_f32_e32 v236, v244, v154
	v_mul_f32_e32 v237, v244, v155
	v_cvt_pk_bf16_f32 v234, v234, v235
	v_cvt_pk_bf16_f32 v235, v236, v237
	global_store_dwordx2 v248, v[234:235], s[92:93] offset:160
	v_mul_f32_e32 v230, v244, v156
	v_mul_f32_e32 v231, v244, v157
	v_mul_f32_e32 v232, v244, v158
	v_mul_f32_e32 v233, v244, v159
	v_cvt_pk_bf16_f32 v230, v230, v231
	v_cvt_pk_bf16_f32 v231, v232, v233
	global_store_dwordx2 v248, v[230:231], s[92:93] offset:192
	v_mul_f32_e32 v234, v244, v160
	v_mul_f32_e32 v235, v244, v161
	v_mul_f32_e32 v236, v244, v162
	v_mul_f32_e32 v237, v244, v163
	v_cvt_pk_bf16_f32 v234, v234, v235
	v_cvt_pk_bf16_f32 v235, v236, v237
	global_store_dwordx2 v248, v[234:235], s[92:93] offset:224
	v_add_u32_e32 v248, 0x100, v248
	v_mul_f32_e32 v230, v245, v8
	v_mul_f32_e32 v231, v245, v9
	v_mul_f32_e32 v232, v245, v10
	v_mul_f32_e32 v233, v245, v11
	v_cvt_pk_bf16_f32 v230, v230, v231
	v_cvt_pk_bf16_f32 v231, v232, v233
	global_store_dwordx2 v249, v[230:231], s[92:93]
	v_mul_f32_e32 v234, v245, v16
	v_mul_f32_e32 v235, v245, v17
	v_mul_f32_e32 v236, v245, v18
	v_mul_f32_e32 v237, v245, v19
	v_cvt_pk_bf16_f32 v234, v234, v235
	v_cvt_pk_bf16_f32 v235, v236, v237
	global_store_dwordx2 v249, v[234:235], s[92:93] offset:32
	v_mul_f32_e32 v230, v245, v24
	v_mul_f32_e32 v231, v245, v25
	v_mul_f32_e32 v232, v245, v26
	v_mul_f32_e32 v233, v245, v27
	v_cvt_pk_bf16_f32 v230, v230, v231
	v_cvt_pk_bf16_f32 v231, v232, v233
	global_store_dwordx2 v249, v[230:231], s[92:93] offset:64
	v_mul_f32_e32 v234, v245, v32
	v_mul_f32_e32 v235, v245, v33
	v_mul_f32_e32 v236, v245, v34
	v_mul_f32_e32 v237, v245, v35
	v_cvt_pk_bf16_f32 v234, v234, v235
	v_cvt_pk_bf16_f32 v235, v236, v237
	global_store_dwordx2 v249, v[234:235], s[92:93] offset:96
	v_mul_f32_e32 v230, v245, v40
	v_mul_f32_e32 v231, v245, v41
	v_mul_f32_e32 v232, v245, v42
	v_mul_f32_e32 v233, v245, v43
	v_cvt_pk_bf16_f32 v230, v230, v231
	v_cvt_pk_bf16_f32 v231, v232, v233
	global_store_dwordx2 v249, v[230:231], s[92:93] offset:128
	v_mul_f32_e32 v234, v245, v48
	v_mul_f32_e32 v235, v245, v49
	v_mul_f32_e32 v236, v245, v50
	v_mul_f32_e32 v237, v245, v51
	v_cvt_pk_bf16_f32 v234, v234, v235
	v_cvt_pk_bf16_f32 v235, v236, v237
	global_store_dwordx2 v249, v[234:235], s[92:93] offset:160
	v_mul_f32_e32 v230, v245, v56
	v_mul_f32_e32 v231, v245, v57
	v_mul_f32_e32 v232, v245, v58
	v_mul_f32_e32 v233, v245, v59
	v_cvt_pk_bf16_f32 v230, v230, v231
	v_cvt_pk_bf16_f32 v231, v232, v233
	global_store_dwordx2 v249, v[230:231], s[92:93] offset:192
	v_mul_f32_e32 v234, v245, v64
	v_mul_f32_e32 v235, v245, v65
	v_mul_f32_e32 v236, v245, v66
	v_mul_f32_e32 v237, v245, v67
	v_cvt_pk_bf16_f32 v234, v234, v235
	v_cvt_pk_bf16_f32 v235, v236, v237
	global_store_dwordx2 v249, v[234:235], s[92:93] offset:224
	v_add_u32_e32 v249, 0x100, v249
	v_xor_b32_e32 v196, 0x10000, v196
	v_xor_b32_e32 v197, 0x10000, v197
	v_xor_b32_e32 v198, 0x10000, v198
	v_xor_b32_e32 v199, 0x10000, v199
	v_xor_b32_e32 v200, 0x10000, v200
	v_xor_b32_e32 v201, 0x10000, v201
	v_xor_b32_e32 v202, 0x10000, v202
	v_xor_b32_e32 v203, 0x10000, v203
	s_add_i32 s4, s4, 1
	s_cmp_lt_u32 s4, 4
	s_cbranch_scc1 .Lxa_pv
	s_waitcnt vmcnt(0)
	s_waitcnt lgkmcnt(0)
	s_barrier
